# hidden FFN buffer stored K-tile-blocked ([panel][ktile][256][64]) so FFN-in writes and FFN-out A-tile reads are contiguous 32KB blocks; V^T rounds reversed
# speedup vs baseline: 1.0337x; 1.0053x over previous
.LBB0_161:
	s_lshl_b32 s1, s1, 12
	s_and_b32 s1, s1, 0x1000
	v_add_u32_e32 v126, s1, v169
	ds_read_b128 v[172:175], v126
	ds_read_b128 v[176:179], v126 offset:256
	ds_read_b128 v[150:153], v126 offset:512
	ds_read_b128 v[146:149], v126 offset:768
	ds_read_b128 v[142:145], v126 offset:2048
	ds_read_b128 v[138:141], v126 offset:2304
	ds_read_b128 v[134:137], v126 offset:2560
	ds_read_b128 v[126:129], v126 offset:2816
	s_waitcnt lgkmcnt(0)
	v_add_f32_e32 v172, v172, v173
	v_add_f32_e32 v173, v174, v175
	v_pk_mul_f32 v[120:121], v[116:117], v[120:121]
	v_add_f32_e32 v172, v172, v173
	v_fmamk_f32 v172, v172, 0x3a800000, v191
	v_rsq_f32_e32 v173, v172
	v_pk_mul_f32 v[132:133], v[124:125], v[132:133]
	v_and_b32_e32 v180, 63, v168
	v_lshrrev_b32_e32 v181, 6, v168
	v_lshl_or_b32 v180, v181, 14, v180
	v_lshl_or_b32 v180, s0, 15, v180
	v_lshl_add_u32 v171, s4, 8, v166
	v_mul_f32_e32 v172, 0xbfb8aa3b, v173
	v_mul_f32_e32 v173, v173, v173
	v_pk_mul_f32 v[182:183], v[122:123], v[172:173] op_sel_hi:[1,0]
	v_pk_mul_f32 v[122:123], v[122:123], v[130:131]
	v_pk_mul_f32 v[130:131], v[114:115], v[172:173] op_sel_hi:[1,0]
	v_rcp_f32_e32 v174, v173
	v_exp_f32_e32 v130, v130
	v_exp_f32_e32 v131, v131
	v_pk_mul_f32 v[116:117], v[116:117], v[172:173] op_sel_hi:[1,0]
	v_exp_f32_e32 v182, v182
	v_exp_f32_e32 v183, v183
	v_pk_mul_f32 v[124:125], v[124:125], v[172:173] op_sel_hi:[1,0]
	v_exp_f32_e32 v116, v116
	v_exp_f32_e32 v117, v117
	v_exp_f32_e32 v124, v124
	v_exp_f32_e32 v125, v125
	v_pk_fma_f32 v[130:131], v[174:175], v[130:131], v[174:175] op_sel_hi:[0,1,0]
	v_pk_fma_f32 v[182:183], v[174:175], v[182:183], v[174:175] op_sel_hi:[0,1,0]
	v_rcp_f32_e32 v130, v130
	v_rcp_f32_e32 v131, v131
	v_pk_fma_f32 v[116:117], v[174:175], v[116:117], v[174:175] op_sel_hi:[0,1,0]
	v_rcp_f32_e32 v182, v182
	v_rcp_f32_e32 v183, v183
	v_pk_fma_f32 v[124:125], v[174:175], v[124:125], v[174:175] op_sel_hi:[0,1,0]
	v_rcp_f32_e32 v116, v116
	v_rcp_f32_e32 v117, v117
	v_rcp_f32_e32 v124, v124
	v_rcp_f32_e32 v125, v125
	v_pk_mul_f32 v[114:115], v[114:115], v[118:119]
	v_ashrrev_i32_e32 v181, 31, v180
	v_pk_mul_f32 v[114:115], v[114:115], v[130:131]
	v_pk_mul_f32 v[122:123], v[122:123], v[182:183]
	v_pk_mul_f32 v[116:117], v[120:121], v[116:117]
	v_cvt_pk_bf16_f32 v120, v114, v115
	s_mul_i32 s100, s4, 0x158000
	s_add_u32 s100, s16, s100
	s_addc_u32 s101, s17, 0
	v_mov_b64_e32 v[114:115], s[100:101]
	v_pk_mul_f32 v[124:125], v[132:133], v[124:125]
	v_cvt_pk_bf16_f32 v118, v122, v123
	v_cvt_pk_bf16_f32 v121, v116, v117
	v_mad_i64_i32 v[122:123], s[0:1], v171, s70, v[114:115]
	v_lshlrev_b64 v[116:117], 1, v[180:181]
	v_cvt_pk_bf16_f32 v119, v124, v125
	v_lshl_add_u64 v[122:123], v[122:123], 0, v[116:117]
	global_store_dwordx4 v[122:123], v[118:121], off
	v_pk_mul_f32 v[112:113], v[108:109], v[112:113]
	v_pk_mul_f32 v[104:105], v[100:101], v[104:105]
	v_add_f32_e32 v118, v176, v177
	v_add_f32_e32 v119, v178, v179
	v_pk_mul_f32 v[96:97], v[92:93], v[96:97]
	v_add_f32_e32 v118, v118, v119
	v_fmamk_f32 v118, v118, 0x3a800000, v191
	v_rsq_f32_e32 v119, v118
	v_pk_mul_f32 v[88:89], v[84:85], v[88:89]
	v_pk_mul_f32 v[80:81], v[76:77], v[80:81]
	v_pk_mul_f32 v[72:73], v[68:69], v[72:73]
	v_mul_f32_e32 v118, 0xbfb8aa3b, v119
	v_mul_f32_e32 v119, v119, v119
	v_pk_mul_f32 v[122:123], v[106:107], v[118:119] op_sel_hi:[1,0]
	v_pk_mul_f32 v[106:107], v[106:107], v[110:111]
	v_pk_mul_f32 v[110:111], v[98:99], v[118:119] op_sel_hi:[1,0]
	v_rcp_f32_e32 v120, v119
	v_exp_f32_e32 v110, v110
	v_exp_f32_e32 v111, v111
	v_pk_mul_f32 v[98:99], v[98:99], v[102:103]
	v_pk_mul_f32 v[108:109], v[108:109], v[118:119] op_sel_hi:[1,0]
	v_exp_f32_e32 v122, v122
	v_pk_fma_f32 v[110:111], v[120:121], v[110:111], v[120:121] op_sel_hi:[0,1,0]
	v_rcp_f32_e32 v110, v110
	v_rcp_f32_e32 v111, v111
	v_exp_f32_e32 v123, v123
	v_exp_f32_e32 v108, v108
	v_exp_f32_e32 v109, v109
	v_pk_mul_f32 v[102:103], v[98:99], v[110:111]
	v_pk_mul_f32 v[98:99], v[100:101], v[118:119] op_sel_hi:[1,0]
	v_pk_fma_f32 v[122:123], v[120:121], v[122:123], v[120:121] op_sel_hi:[0,1,0]
	v_exp_f32_e32 v98, v98
	v_exp_f32_e32 v99, v99
	v_pk_fma_f32 v[108:109], v[120:121], v[108:109], v[120:121] op_sel_hi:[0,1,0]
	v_rcp_f32_e32 v122, v122
	v_rcp_f32_e32 v123, v123
	v_pk_fma_f32 v[98:99], v[120:121], v[98:99], v[120:121] op_sel_hi:[0,1,0]
	v_rcp_f32_e32 v108, v108
	v_rcp_f32_e32 v109, v109
	v_rcp_f32_e32 v98, v98
	v_rcp_f32_e32 v99, v99
	v_or_b32_e32 v110, 16, v171
	v_pk_mul_f32 v[106:107], v[106:107], v[122:123]
	v_pk_mul_f32 v[108:109], v[112:113], v[108:109]
	v_pk_mul_f32 v[104:105], v[104:105], v[98:99]
	v_cvt_pk_bf16_f32 v100, v102, v103
	v_mad_i64_i32 v[102:103], s[0:1], v110, s70, v[114:115]
	v_cvt_pk_bf16_f32 v98, v106, v107
	v_cvt_pk_bf16_f32 v99, v108, v109
	v_cvt_pk_bf16_f32 v101, v104, v105
	v_lshl_add_u64 v[102:103], v[102:103], 0, v[116:117]
	global_store_dwordx4 v[102:103], v[98:101], off
	v_pk_mul_f32 v[64:65], v[60:61], v[64:65]
	v_pk_mul_f32 v[56:57], v[52:53], v[56:57]
	v_add_f32_e32 v98, v150, v151
	v_add_f32_e32 v99, v152, v153
	v_pk_mul_f32 v[46:47], v[42:43], v[46:47]
	v_add_f32_e32 v98, v98, v99
	v_fmamk_f32 v98, v98, 0x3a800000, v191
	v_rsq_f32_e32 v99, v98
	v_pk_mul_f32 v[38:39], v[34:35], v[38:39]
	v_pk_mul_f32 v[30:31], v[26:27], v[30:31]
	v_pk_mul_f32 v[22:23], v[18:19], v[22:23]
	v_mul_f32_e32 v98, 0xbfb8aa3b, v99
	v_mul_f32_e32 v99, v99, v99
	v_pk_mul_f32 v[102:103], v[90:91], v[98:99] op_sel_hi:[1,0]
	v_pk_mul_f32 v[90:91], v[90:91], v[94:95]
	v_pk_mul_f32 v[94:95], v[82:83], v[98:99] op_sel_hi:[1,0]
	v_rcp_f32_e32 v100, v99
	v_exp_f32_e32 v94, v94
	v_exp_f32_e32 v95, v95
	v_pk_mul_f32 v[82:83], v[82:83], v[86:87]
	v_pk_mul_f32 v[92:93], v[92:93], v[98:99] op_sel_hi:[1,0]
	v_exp_f32_e32 v102, v102
	v_pk_fma_f32 v[94:95], v[100:101], v[94:95], v[100:101] op_sel_hi:[0,1,0]
	v_rcp_f32_e32 v94, v94
	v_rcp_f32_e32 v95, v95
	v_exp_f32_e32 v103, v103
	v_exp_f32_e32 v92, v92
	v_exp_f32_e32 v93, v93
	v_pk_mul_f32 v[86:87], v[82:83], v[94:95]
	v_pk_mul_f32 v[82:83], v[84:85], v[98:99] op_sel_hi:[1,0]
	v_pk_fma_f32 v[102:103], v[100:101], v[102:103], v[100:101] op_sel_hi:[0,1,0]
	v_exp_f32_e32 v82, v82
	v_exp_f32_e32 v83, v83
	v_pk_fma_f32 v[92:93], v[100:101], v[92:93], v[100:101] op_sel_hi:[0,1,0]
	v_rcp_f32_e32 v102, v102
	v_rcp_f32_e32 v103, v103
	v_pk_fma_f32 v[82:83], v[100:101], v[82:83], v[100:101] op_sel_hi:[0,1,0]
	v_rcp_f32_e32 v92, v92
	v_rcp_f32_e32 v93, v93
	v_rcp_f32_e32 v82, v82
	v_rcp_f32_e32 v83, v83
	v_or_b32_e32 v94, 32, v171
	v_pk_mul_f32 v[90:91], v[90:91], v[102:103]
	v_pk_mul_f32 v[92:93], v[96:97], v[92:93]
	v_pk_mul_f32 v[88:89], v[88:89], v[82:83]
	v_cvt_pk_bf16_f32 v84, v86, v87
	v_mad_i64_i32 v[86:87], s[0:1], v94, s70, v[114:115]
	v_cvt_pk_bf16_f32 v82, v90, v91
	v_cvt_pk_bf16_f32 v83, v92, v93
	v_cvt_pk_bf16_f32 v85, v88, v89
	v_lshl_add_u64 v[86:87], v[86:87], 0, v[116:117]
	global_store_dwordx4 v[86:87], v[82:85], off
	v_pk_mul_f32 v[14:15], v[10:11], v[14:15]
	v_pk_mul_f32 v[6:7], v[2:3], v[6:7]
	v_add_f32_e32 v82, v146, v147
	v_add_f32_e32 v83, v148, v149
	s_mov_b64 s[28:29], -1
	v_add_f32_e32 v82, v82, v83
	v_fmamk_f32 v82, v82, 0x3a800000, v191
	v_rsq_f32_e32 v83, v82
	s_andn2_b64 vcc, exec, s[8:9]
	v_mul_f32_e32 v82, 0xbfb8aa3b, v83
	v_mul_f32_e32 v83, v83, v83
	v_pk_mul_f32 v[86:87], v[74:75], v[82:83] op_sel_hi:[1,0]
	v_pk_mul_f32 v[74:75], v[74:75], v[78:79]
	v_pk_mul_f32 v[78:79], v[66:67], v[82:83] op_sel_hi:[1,0]
	v_rcp_f32_e32 v84, v83
	v_exp_f32_e32 v78, v78
	v_exp_f32_e32 v79, v79
	v_pk_mul_f32 v[66:67], v[66:67], v[70:71]
	v_pk_mul_f32 v[76:77], v[76:77], v[82:83] op_sel_hi:[1,0]
	v_exp_f32_e32 v86, v86
	v_pk_fma_f32 v[78:79], v[84:85], v[78:79], v[84:85] op_sel_hi:[0,1,0]
	v_rcp_f32_e32 v78, v78
	v_rcp_f32_e32 v79, v79
	v_exp_f32_e32 v87, v87
	v_exp_f32_e32 v76, v76
	v_exp_f32_e32 v77, v77
	v_pk_mul_f32 v[70:71], v[66:67], v[78:79]
	v_pk_mul_f32 v[66:67], v[68:69], v[82:83] op_sel_hi:[1,0]
	v_pk_fma_f32 v[86:87], v[84:85], v[86:87], v[84:85] op_sel_hi:[0,1,0]
	v_exp_f32_e32 v66, v66
	v_exp_f32_e32 v67, v67
	v_pk_fma_f32 v[76:77], v[84:85], v[76:77], v[84:85] op_sel_hi:[0,1,0]
	v_rcp_f32_e32 v86, v86
	v_rcp_f32_e32 v87, v87
	v_pk_fma_f32 v[66:67], v[84:85], v[66:67], v[84:85] op_sel_hi:[0,1,0]
	v_rcp_f32_e32 v76, v76
	v_rcp_f32_e32 v77, v77
	v_rcp_f32_e32 v66, v66
	v_rcp_f32_e32 v67, v67
	v_or_b32_e32 v78, 48, v171
	v_pk_mul_f32 v[74:75], v[74:75], v[86:87]
	v_pk_mul_f32 v[76:77], v[80:81], v[76:77]
	v_pk_mul_f32 v[72:73], v[72:73], v[66:67]
	v_cvt_pk_bf16_f32 v68, v70, v71
	v_mad_i64_i32 v[70:71], s[0:1], v78, s70, v[114:115]
	v_cvt_pk_bf16_f32 v66, v74, v75
	v_cvt_pk_bf16_f32 v67, v76, v77
	v_cvt_pk_bf16_f32 v69, v72, v73
	v_lshl_add_u64 v[70:71], v[70:71], 0, v[116:117]
	global_store_dwordx4 v[70:71], v[66:69], off
	s_nop 1
	v_add_f32_e32 v66, v142, v143
	v_add_f32_e32 v68, v144, v145
	v_add_u32_e32 v67, 0x80, v171
	v_add_f32_e32 v66, v66, v68
	v_fmamk_f32 v66, v66, 0x3a800000, v191
	v_rsq_f32_e32 v68, v66
	s_nop 0
	v_mul_f32_e32 v66, 0xbfb8aa3b, v68
	v_mul_f32_e32 v68, v68, v68
	v_pk_mul_f32 v[70:71], v[58:59], v[66:67] op_sel_hi:[1,0]
	v_pk_mul_f32 v[58:59], v[58:59], v[62:63]
	v_pk_mul_f32 v[62:63], v[50:51], v[66:67] op_sel_hi:[1,0]
	v_rcp_f32_e32 v68, v68
	v_exp_f32_e32 v62, v62
	v_exp_f32_e32 v63, v63
	v_pk_mul_f32 v[50:51], v[50:51], v[54:55]
	v_pk_mul_f32 v[60:61], v[60:61], v[66:67] op_sel_hi:[1,0]
	v_exp_f32_e32 v70, v70
	v_pk_fma_f32 v[62:63], v[68:69], v[62:63], v[68:69] op_sel_hi:[0,1,0]
	v_rcp_f32_e32 v62, v62
	v_rcp_f32_e32 v63, v63
	v_exp_f32_e32 v71, v71
	v_exp_f32_e32 v60, v60
	v_exp_f32_e32 v61, v61
	v_pk_mul_f32 v[54:55], v[50:51], v[62:63]
	v_pk_mul_f32 v[50:51], v[52:53], v[66:67] op_sel_hi:[1,0]
	v_pk_fma_f32 v[70:71], v[68:69], v[70:71], v[68:69] op_sel_hi:[0,1,0]
	v_exp_f32_e32 v50, v50
	v_exp_f32_e32 v51, v51
	v_pk_fma_f32 v[60:61], v[68:69], v[60:61], v[68:69] op_sel_hi:[0,1,0]
	v_rcp_f32_e32 v70, v70
	v_rcp_f32_e32 v71, v71
	v_pk_fma_f32 v[50:51], v[68:69], v[50:51], v[68:69] op_sel_hi:[0,1,0]
	v_rcp_f32_e32 v60, v60
	v_rcp_f32_e32 v61, v61
	v_rcp_f32_e32 v50, v50
	v_rcp_f32_e32 v51, v51
	v_pk_mul_f32 v[58:59], v[58:59], v[70:71]
	v_pk_mul_f32 v[60:61], v[64:65], v[60:61]
	v_cvt_pk_bf16_f32 v52, v54, v55
	v_pk_mul_f32 v[56:57], v[56:57], v[50:51]
	v_mad_i64_i32 v[54:55], s[0:1], v67, s70, v[114:115]
	v_cvt_pk_bf16_f32 v50, v58, v59
	v_cvt_pk_bf16_f32 v51, v60, v61
	v_cvt_pk_bf16_f32 v53, v56, v57
	v_lshl_add_u64 v[54:55], v[54:55], 0, v[116:117]
	global_store_dwordx4 v[54:55], v[50:53], off
	s_nop 1
	v_add_f32_e32 v50, v138, v139
	v_add_f32_e32 v51, v140, v141
	s_nop 0
	v_add_f32_e32 v50, v50, v51
	v_fmamk_f32 v50, v50, 0x3a800000, v191
	v_rsq_f32_e32 v51, v50
	s_nop 0
	v_mul_f32_e32 v50, 0xbfb8aa3b, v51
	v_mul_f32_e32 v51, v51, v51
	v_pk_mul_f32 v[54:55], v[40:41], v[50:51] op_sel_hi:[1,0]
	v_pk_mul_f32 v[40:41], v[40:41], v[44:45]
	v_pk_mul_f32 v[44:45], v[32:33], v[50:51] op_sel_hi:[1,0]
	v_rcp_f32_e32 v52, v51
	v_exp_f32_e32 v44, v44
	v_exp_f32_e32 v45, v45
	v_pk_mul_f32 v[32:33], v[32:33], v[36:37]
	v_pk_mul_f32 v[42:43], v[42:43], v[50:51] op_sel_hi:[1,0]
	v_exp_f32_e32 v54, v54
	v_pk_fma_f32 v[44:45], v[52:53], v[44:45], v[52:53] op_sel_hi:[0,1,0]
	v_rcp_f32_e32 v44, v44
	v_rcp_f32_e32 v45, v45
	v_exp_f32_e32 v55, v55
	v_exp_f32_e32 v42, v42
	v_exp_f32_e32 v43, v43
	v_pk_mul_f32 v[36:37], v[32:33], v[44:45]
	v_pk_mul_f32 v[32:33], v[34:35], v[50:51] op_sel_hi:[1,0]
	v_pk_fma_f32 v[54:55], v[52:53], v[54:55], v[52:53] op_sel_hi:[0,1,0]
	v_exp_f32_e32 v32, v32
	v_exp_f32_e32 v33, v33
	v_pk_fma_f32 v[42:43], v[52:53], v[42:43], v[52:53] op_sel_hi:[0,1,0]
	v_rcp_f32_e32 v54, v54
	v_rcp_f32_e32 v55, v55
	v_pk_fma_f32 v[32:33], v[52:53], v[32:33], v[52:53] op_sel_hi:[0,1,0]
	v_rcp_f32_e32 v42, v42
	v_rcp_f32_e32 v43, v43
	v_rcp_f32_e32 v32, v32
	v_rcp_f32_e32 v33, v33
	v_add_u32_e32 v44, 0x90, v171
	v_pk_mul_f32 v[40:41], v[40:41], v[54:55]
	v_pk_mul_f32 v[42:43], v[46:47], v[42:43]
	v_pk_mul_f32 v[38:39], v[38:39], v[32:33]
	v_cvt_pk_bf16_f32 v34, v36, v37
	v_mad_i64_i32 v[36:37], s[0:1], v44, s70, v[114:115]
	v_cvt_pk_bf16_f32 v32, v40, v41
	v_cvt_pk_bf16_f32 v33, v42, v43
	v_cvt_pk_bf16_f32 v35, v38, v39
	v_lshl_add_u64 v[36:37], v[36:37], 0, v[116:117]
	global_store_dwordx4 v[36:37], v[32:35], off
	s_nop 1
	v_add_f32_e32 v32, v134, v135
	v_add_f32_e32 v33, v136, v137
	s_nop 0
	v_add_f32_e32 v32, v32, v33
	v_fmamk_f32 v32, v32, 0x3a800000, v191
	v_rsq_f32_e32 v33, v32
	s_nop 0
	v_mul_f32_e32 v32, 0xbfb8aa3b, v33
	v_mul_f32_e32 v33, v33, v33
	v_pk_mul_f32 v[36:37], v[24:25], v[32:33] op_sel_hi:[1,0]
	v_pk_mul_f32 v[24:25], v[24:25], v[28:29]
	v_pk_mul_f32 v[28:29], v[16:17], v[32:33] op_sel_hi:[1,0]
	v_rcp_f32_e32 v34, v33
	v_exp_f32_e32 v28, v28
	v_exp_f32_e32 v29, v29
	v_pk_mul_f32 v[16:17], v[16:17], v[20:21]
	v_pk_mul_f32 v[26:27], v[26:27], v[32:33] op_sel_hi:[1,0]
	v_exp_f32_e32 v36, v36
	v_pk_fma_f32 v[28:29], v[34:35], v[28:29], v[34:35] op_sel_hi:[0,1,0]
	v_rcp_f32_e32 v28, v28
	v_rcp_f32_e32 v29, v29
	v_exp_f32_e32 v37, v37
	v_exp_f32_e32 v26, v26
	v_exp_f32_e32 v27, v27
	v_pk_mul_f32 v[20:21], v[16:17], v[28:29]
	v_pk_mul_f32 v[16:17], v[18:19], v[32:33] op_sel_hi:[1,0]
	v_pk_fma_f32 v[36:37], v[34:35], v[36:37], v[34:35] op_sel_hi:[0,1,0]
	v_exp_f32_e32 v16, v16
	v_exp_f32_e32 v17, v17
	v_pk_fma_f32 v[26:27], v[34:35], v[26:27], v[34:35] op_sel_hi:[0,1,0]
	v_rcp_f32_e32 v36, v36
	v_rcp_f32_e32 v37, v37
	v_pk_fma_f32 v[16:17], v[34:35], v[16:17], v[34:35] op_sel_hi:[0,1,0]
	v_rcp_f32_e32 v26, v26
	v_rcp_f32_e32 v27, v27
	v_rcp_f32_e32 v16, v16
	v_rcp_f32_e32 v17, v17
	v_add_u32_e32 v28, 0xa0, v171
	v_pk_mul_f32 v[24:25], v[24:25], v[36:37]
	v_pk_mul_f32 v[26:27], v[30:31], v[26:27]
	v_pk_mul_f32 v[22:23], v[22:23], v[16:17]
	v_cvt_pk_bf16_f32 v18, v20, v21
	v_mad_i64_i32 v[20:21], s[0:1], v28, s70, v[114:115]
	v_cvt_pk_bf16_f32 v16, v24, v25
	v_cvt_pk_bf16_f32 v17, v26, v27
	v_cvt_pk_bf16_f32 v19, v22, v23
	v_lshl_add_u64 v[20:21], v[20:21], 0, v[116:117]
	global_store_dwordx4 v[20:21], v[16:19], off
	s_nop 1
	v_add_f32_e32 v16, v126, v127
	v_add_f32_e32 v17, v128, v129
	s_nop 0
	v_add_f32_e32 v16, v16, v17
	v_fmamk_f32 v16, v16, 0x3a800000, v191
	v_rsq_f32_e32 v17, v16
	s_nop 0
	v_mul_f32_e32 v16, 0xbfb8aa3b, v17
	v_mul_f32_e32 v17, v17, v17
	v_pk_mul_f32 v[20:21], v[8:9], v[16:17] op_sel_hi:[1,0]
	v_pk_mul_f32 v[8:9], v[8:9], v[12:13]
	v_pk_mul_f32 v[12:13], v[0:1], v[16:17] op_sel_hi:[1,0]
	v_rcp_f32_e32 v18, v17
	v_exp_f32_e32 v12, v12
	v_exp_f32_e32 v13, v13
	v_pk_mul_f32 v[0:1], v[0:1], v[4:5]
	v_pk_mul_f32 v[10:11], v[10:11], v[16:17] op_sel_hi:[1,0]
	v_exp_f32_e32 v20, v20
	v_pk_fma_f32 v[12:13], v[18:19], v[12:13], v[18:19] op_sel_hi:[0,1,0]
	v_rcp_f32_e32 v12, v12
	v_rcp_f32_e32 v13, v13
	v_exp_f32_e32 v21, v21
	v_exp_f32_e32 v10, v10
	v_exp_f32_e32 v11, v11
	v_pk_mul_f32 v[4:5], v[0:1], v[12:13]
	v_pk_mul_f32 v[0:1], v[2:3], v[16:17] op_sel_hi:[1,0]
	v_pk_fma_f32 v[20:21], v[18:19], v[20:21], v[18:19] op_sel_hi:[0,1,0]
	v_exp_f32_e32 v0, v0
	v_exp_f32_e32 v1, v1
	v_pk_fma_f32 v[10:11], v[18:19], v[10:11], v[18:19] op_sel_hi:[0,1,0]
	v_rcp_f32_e32 v20, v20
	v_rcp_f32_e32 v21, v21
	v_pk_fma_f32 v[0:1], v[18:19], v[0:1], v[18:19] op_sel_hi:[0,1,0]
	v_rcp_f32_e32 v10, v10
	v_rcp_f32_e32 v11, v11
	v_rcp_f32_e32 v0, v0
	v_rcp_f32_e32 v1, v1
	v_add_u32_e32 v12, 0xb0, v171
	v_pk_mul_f32 v[8:9], v[8:9], v[20:21]
	v_pk_mul_f32 v[10:11], v[14:15], v[10:11]
	v_pk_mul_f32 v[6:7], v[6:7], v[0:1]
	v_cvt_pk_bf16_f32 v2, v4, v5
	v_mad_i64_i32 v[4:5], s[0:1], v12, s70, v[114:115]
	v_cvt_pk_bf16_f32 v0, v8, v9
	v_cvt_pk_bf16_f32 v1, v10, v11
	v_cvt_pk_bf16_f32 v3, v6, v7
	v_lshl_add_u64 v[4:5], v[4:5], 0, v[116:117]
	global_store_dwordx4 v[4:5], v[0:3], off
	s_cbranch_vccnz .LBB0_150
	s_andn2_b64 vcc, exec, s[10:11]
	s_cbranch_vccnz .LBB0_164
	s_lshl_b32 s0, s85, 12
	s_and_b32 s0, s0, 0x1000
	s_add_i32 m0, s82, s0
	s_lshl_b32 s0, s22, 8
	s_add_i32 s0, s0, s83
	s_ashr_i32 s1, s0, 31
	v_lshl_add_u64 v[0:1], s[0:1], 4, v[160:161]
	global_load_lds_dwordx4 v[0:1], off

.LBB0_180:
	s_cmp_eq_u32 s47, 13
	s_cselect_b64 s[12:13], -1, 0
	s_and_b64 s[0:1], s[12:13], exec
	s_cselect_b32 s4, 0x4c00000, s8
	s_cmp_eq_u32 s47, 4
	s_cselect_b64 s[10:11], -1, 0
	s_and_b64 s[0:1], s[10:11], exec
	s_mov_b32 s0, 0x15000000
	s_cselect_b32 s8, 0x5000000, s0
	s_cselect_b32 s4, 0x4e00000, s4
	s_or_b64 s[0:1], s[10:11], s[12:13]
	s_waitcnt lgkmcnt(0)
	s_add_u32 s36, s78, s8
	s_addc_u32 s37, s79, 0
	s_and_b64 s[14:15], s[0:1], exec
	s_cselect_b32 s8, 0, s9
	s_add_u32 s38, s78, s4
	s_addc_u32 s39, s79, s8
	s_and_b64 s[0:1], s[0:1], exec
	s_movk_i32 s0, 0xb00
	s_cselect_b32 s40, 0x400, s0
	s_mov_b32 s100, 0x8000
	s_cselect_b32 s100, 0x80, s100
	s_mov_b32 s101, 0
	s_cmp_eq_u32 s47, 10
	s_cselect_b64 s[0:1], -1, 0
	s_or_b64 s[8:9], s[10:11], s[0:1]
	s_cmp_eq_u32 s47, 15
	s_cselect_b64 s[0:1], -1, 0
	s_or_b64 s[0:1], s[0:1], s[8:9]
	s_and_b64 s[0:1], s[0:1], exec
	s_cselect_b32 s0, s66, 0x5000000
	s_add_u32 s16, s78, s0
	s_addc_u32 s17, s79, 0
	s_cmp_lg_u32 s47, 15
	s_mov_b64 s[14:15], -1
	s_cbranch_scc0 .LBB0_206
	s_and_b64 vcc, exec, s[6:7]
	v_readfirstlane_b32 s0, v237
	s_cbranch_vccnz .LBB0_205
	v_lshlrev_b32_e32 v238, 4, v237
	v_add_u32_e32 v0, 0x2000, v238
	v_ashrrev_i32_e32 v1, 31, v0
	v_lshrrev_b32_e32 v1, 22, v1
	v_add_u32_e32 v1, v0, v1
	v_ashrrev_i32_e32 v1, 10, v1
	v_mul_i32_i24_e32 v2, 0x400, v1
	v_sub_u32_e32 v0, v0, v2
	v_lshrrev_b32_e32 v2, 4, v0
	v_bitop3_b32 v0, v2, v0, 32 bitop3:0x6c
	s_and_b64 s[12:13], s[12:13], exec
	s_movk_i32 s1, 0xb00
	v_ashrrev_i32_e32 v2, 31, v0
	s_cselect_b32 s1, 0x400, s1
	s_and_b64 s[12:13], s[10:11], exec
	v_lshrrev_b32_e32 v2, 26, v2
	s_cselect_b32 s4, 0x100, s1
	s_ashr_i32 s12, s0, 6
	v_add_u32_e32 v2, v0, v2
	v_lshlrev_b32_e32 v4, 3, v1
	s_ashr_i32 s1, s0, 8
	s_movk_i32 s50, 0x4000
	s_cmpk_eq_u32 s100, 0x80
	s_cselect_b32 s50, 0x40000, s50
	s_lshl_b32 s41, s4, 8
	s_lshl_b32 s48, s40, 9
	s_lshr_b32 s40, s50, 8
	s_lshl_b32 s49, s4, 9
	s_lshl_b32 s52, s12, 10
	v_ashrrev_i32_e32 v3, 6, v2
	v_and_b32_e32 v4, -16, v4
	v_lshlrev_b32_e32 v1, 5, v1
	s_and_b64 s[10:11], s[10:11], exec
	v_add_u32_e32 v4, v3, v4
	v_and_b32_e32 v142, 32, v1
	v_and_b32_e32 v1, 0xc0, v2
	v_and_b32_e32 v3, 3, v3
	s_mov_b32 s10, 0xffffe0
	v_lshrrev_b32_e32 v5, 2, v4
	v_lshlrev_b32_e32 v6, 1, v4
	v_sub_u32_e32 v0, v0, v1
	v_and_or_b32 v3, v4, s10, v3
	v_and_b32_e32 v5, 4, v5
	v_and_b32_e32 v6, 24, v6
	v_ashrrev_i16_sdwa v0, v227, sext(v0) dst_sel:DWORD dst_unused:UNUSED_PAD src0_sel:DWORD src1_sel:BYTE_0
	v_or3_b32 v3, v3, v5, v6
	v_bfe_i32 v143, v0, 0, 16
	v_mul_u32_u24_e32 v3, s4, v3
	v_add_u32_e32 v0, v142, v143
	v_mul_lo_u32 v144, v4, s40
	v_add_lshl_u32 v198, v3, v0, 1
	v_add_lshl_u32 v200, v0, v144, 1
	v_bfe_i32 v0, v237, 27, 1
	v_lshrrev_b32_e32 v0, 22, v0
	v_add_u32_e32 v0, v238, v0
	v_and_b32_e32 v0, 0xfffffc00, v0
	v_sub_u32_e32 v0, v238, v0
	v_lshrrev_b32_e32 v1, 4, v0
	v_ashrrev_i32_e32 v3, 31, v237
	v_bitop3_b32 v0, v1, v0, 32 bitop3:0x6c
	v_lshrrev_b32_e32 v3, 26, v3
	v_ashrrev_i32_e32 v1, 31, v0
	v_add_u32_e32 v3, v237, v3
	v_lshrrev_b32_e32 v1, 26, v1
	v_ashrrev_i32_e32 v3, 6, v3
	v_add_u32_e32 v1, v0, v1
	v_lshlrev_b32_e32 v4, 3, v3
	v_ashrrev_i32_e32 v2, 6, v1
	v_and_b32_e32 v4, -16, v4
	v_add_u32_e32 v4, v2, v4
	v_and_b32_e32 v2, 3, v2
	v_and_or_b32 v2, v4, s10, v2
	v_readlane_b32 s10, v254, 36
	v_and_b32_e32 v1, 0xc0, v1
	v_readlane_b32 s11, v254, 37
	s_mov_b32 s14, s10
	s_cselect_b32 s53, 0x200, 0
	v_lshrrev_b32_e32 v5, 2, v4
	v_lshlrev_b32_e32 v6, 1, v4
	v_sub_u32_e32 v0, v0, v1
	s_mul_i32 s11, s48, s14
	v_readlane_b32 s14, v254, 38
	v_and_b32_e32 v5, 4, v5
	v_and_b32_e32 v6, 24, v6
	v_lshlrev_b32_e32 v3, 5, v3
	v_ashrrev_i16_sdwa v0, v227, sext(v0) dst_sel:DWORD dst_unused:UNUSED_PAD src0_sel:DWORD src1_sel:BYTE_0
	s_mul_i32 s13, s53, s14
	s_mul_i32 s14, s49, s14
	v_or3_b32 v2, v2, v5, v6
	v_and_b32_e32 v145, 32, v3
	v_bfe_i32 v146, v0, 0, 16
	s_add_u32 s30, s38, s14
	v_mul_u32_u24_e32 v2, s4, v2
	v_add_u32_e32 v0, v145, v146
	s_addc_u32 s31, s39, 0
	s_add_i32 s82, s52, 0
	v_add_lshl_u32 v48, v2, v0, 1
	v_mul_lo_u32 v147, v4, s40
	s_add_i32 m0, s82, 0x10000
	v_add_lshl_u32 v202, v0, v147, 1
	v_mov_b64 v[126:127], 0
	v_mov_b64 v[128:129], 0
	v_mov_b64 v[122:123], 0
	v_mov_b64 v[124:125], 0
	v_mov_b64 v[110:111], 0
	v_mov_b64 v[112:113], 0
	v_mov_b64 v[98:99], 0
	v_mov_b64 v[100:101], 0
	v_mov_b64 v[94:95], 0
	v_mov_b64 v[96:97], 0
	v_mov_b64 v[82:83], 0
	v_mov_b64 v[84:85], 0
	v_mov_b64 v[78:79], 0
	v_mov_b64 v[80:81], 0
	v_mov_b64 v[66:67], 0
	v_mov_b64 v[68:69], 0
	v_mov_b64 v[118:119], 0
	v_mov_b64 v[120:121], 0
	v_mov_b64 v[114:115], 0
	v_mov_b64 v[116:117], 0
	v_mov_b64 v[106:107], 0
	v_mov_b64 v[108:109], 0
	v_mov_b64 v[102:103], 0
	v_mov_b64 v[104:105], 0
	v_mov_b64 v[90:91], 0
	v_mov_b64 v[92:93], 0
	v_mov_b64 v[86:87], 0
	v_mov_b64 v[88:89], 0
	v_mov_b64 v[74:75], 0
	v_mov_b64 v[76:77], 0
	v_mov_b64 v[70:71], 0
	v_mov_b64 v[72:73], 0
	v_mov_b64 v[62:63], 0
	v_mov_b64 v[64:65], 0
	v_mov_b64 v[50:51], 0
	v_mov_b64 v[52:53], 0
	v_mov_b64 v[44:45], 0
	v_mov_b64 v[46:47], 0
	v_mov_b64 v[32:33], 0
	v_mov_b64 v[34:35], 0
	v_mov_b64 v[28:29], 0
	v_mov_b64 v[30:31], 0
	v_mov_b64 v[16:17], 0
	v_mov_b64 v[18:19], 0
	v_mov_b64 v[12:13], 0
	v_mov_b64 v[14:15], 0
	v_mov_b64 v[0:1], 0
	v_mov_b64 v[2:3], 0
	v_mov_b64 v[58:59], 0
	v_mov_b64 v[60:61], 0
	v_mov_b64 v[54:55], 0
	v_mov_b64 v[56:57], 0
	v_mov_b64 v[40:41], 0
	v_mov_b64 v[42:43], 0
	v_mov_b64 v[36:37], 0
	v_mov_b64 v[38:39], 0
	v_mov_b64 v[24:25], 0
	v_mov_b64 v[26:27], 0
	v_mov_b64 v[20:21], 0
	v_mov_b64 v[22:23], 0
	v_mov_b64 v[8:9], 0
	v_mov_b64 v[10:11], 0
	v_mov_b64 v[4:5], 0
	v_mov_b64 v[6:7], 0
	global_load_lds_dwordx4 v48, s[30:31]
	s_add_i32 m0, s82, 0x12000
	s_mul_hi_i32 s10, s48, s10
	s_add_u32 s14, s36, s11
	s_addc_u32 s15, s37, s10
	s_add_u32 s10, s30, s41
	global_load_lds_dwordx4 v198, s[30:31]
	s_addc_u32 s11, s31, 0
	s_add_i32 m0, s82, 0x14000
	v_mov_b32_e32 v199, v49
	global_load_lds_dwordx4 v48, s[10:11]
	s_add_i32 m0, s82, 0x16000
	s_add_u32 s34, s14, s13
	s_addc_u32 s35, s15, 0
	s_add_i32 s83, s82, 0x2000
	v_lshl_add_u64 v[134:135], s[10:11], 0, v[48:49]
	v_lshl_add_u64 v[136:137], s[10:11], 0, v[198:199]
	global_load_lds_dwordx4 v198, s[10:11]
	s_mov_b32 m0, s82
	s_add_u32 s10, s34, s50
	global_load_lds_dwordx4 v202, s[34:35]
	s_mov_b32 m0, s83
	s_addc_u32 s11, s35, 0
	s_add_i32 s84, s82, 0x4000
	global_load_lds_dwordx4 v200, s[34:35]
	s_mov_b32 m0, s84
	s_add_i32 s85, s82, 0x6000
	global_load_lds_dwordx4 v202, s[10:11]
	s_mov_b32 m0, s85
	v_mov_b32_e32 v203, v49
	global_load_lds_dwordx4 v200, s[10:11]
	v_mov_b32_e32 v201, v49
	s_cmp_eq_u32 s1, 1
	s_mov_b32 s54, s86
	v_lshl_add_u64 v[130:131], s[30:31], 0, v[48:49]
	v_lshl_add_u64 v[132:133], s[30:31], 0, v[198:199]
	v_lshl_add_u64 v[138:139], s[34:35], 0, v[202:203]
	v_lshl_add_u64 v[140:141], s[34:35], 0, v[200:201]
	s_cselect_b64 s[18:19], -1, 0
	s_cmp_lg_u32 s1, 1
	s_cbranch_scc1 .LBB0_184
	s_barrier
.LBB0_184:
	s_and_b64 s[10:11], s[8:9], exec
	s_cselect_b32 s10, 0x5000000, s66
	s_add_u32 s20, s78, s10
	s_addc_u32 s21, s79, 0
	s_and_b64 s[8:9], s[8:9], exec
	s_cselect_b32 s8, 0, 0x100000
	s_add_u32 s22, s78, s8
	s_addc_u32 s23, s79, 0
	s_add_i32 m0, s82, 0x18000
	v_lshl_add_u64 v[130:131], v[130:131], 0, s[70:71]
	s_waitcnt vmcnt(2)
	s_barrier
	global_load_lds_dwordx4 v[130:131], off
	v_lshl_add_u64 v[130:131], v[132:133], 0, s[70:71]
	s_add_i32 m0, s82, 0x1a000
	s_add_i32 s86, s82, 0x8000
	global_load_lds_dwordx4 v[130:131], off
	v_lshl_add_u64 v[130:131], v[138:139], 0, s[100:101]
	s_mov_b32 m0, s86
	s_add_i32 s87, s82, 0xa000
	global_load_lds_dwordx4 v[130:131], off
	v_lshl_add_u64 v[130:131], v[140:141], 0, s[100:101]
	s_mov_b32 m0, s87
	s_and_b32 s10, s12, 3
	global_load_lds_dwordx4 v[130:131], off
	s_add_i32 m0, s82, 0x1c000
	v_lshl_add_u64 v[130:131], v[134:135], 0, s[70:71]
	global_load_lds_dwordx4 v[130:131], off
	v_lshl_add_u64 v[130:131], v[136:137], 0, s[70:71]
	s_add_i32 m0, s82, 0x1e000
	v_lshlrev_b32_e32 v134, 2, v237
	global_load_lds_dwordx4 v[130:131], off
	v_bfe_u32 v130, v237, 4, 2
	v_and_b32_e32 v131, 15, v237
	v_lshlrev_b32_e32 v133, 4, v130
	s_lshr_b32 s89, s4, 6
	s_lshl_b32 s4, s1, 6
	v_lshl_or_b32 v133, v131, 6, v133
	s_lshl_b32 s1, s1, 13
	v_and_b32_e32 v134, 32, v134
	v_bitop3_b32 v135, v133, s1, v134 bitop3:0xde
	s_lshl_b32 s1, s10, 12
	s_add_i32 s90, s89, -2
	s_cmpk_lt_u32 s0, 0x100
	v_bitop3_b32 v240, s1, v133, v134 bitop3:0xf6
	s_cselect_b64 s[24:25], -1, 0
	s_add_i32 s1, s4, 0x80
	v_lshlrev_b32_e32 v132, 3, v130
	v_cmp_eq_u32_e64 s[8:9], 0, v130
	v_or_b32_e32 v130, s1, v131
	s_add_i32 s1, s4, 0x90
	v_lshlrev_b32_e32 v133, 4, v130
	v_or_b32_e32 v130, s1, v131
	s_add_i32 s1, s4, 0xa0
	v_or_b32_e32 v239, s4, v131
	v_lshlrev_b32_e32 v134, 4, v130
	v_or_b32_e32 v130, s1, v131
	s_addk_i32 s4, 0xb0
	v_lshlrev_b32_e32 v136, 4, v130
	v_or_b32_e32 v130, s4, v131
	s_lshl_b32 s0, s10, 2
	v_lshlrev_b32_e32 v137, 4, v130
	v_add_u32_e32 v130, v147, v145
	s_add_i32 s0, s0, 0
	v_add_lshl_u32 v130, v130, v146, 1
	v_mov_b32_e32 v131, v49
	s_waitcnt vmcnt(6)
	v_lshl_or_b32 v241, s10, 5, v132
	s_add_i32 s0, s0, 0x20000
	v_lshlrev_b32_e32 v132, 4, v239
	v_lshl_add_u64 v[204:205], s[50:51], 0, v[130:131]
	v_add_u32_e32 v130, v144, v142
	s_movk_i32 s1, 0x100
	v_add_lshl_u32 v130, v130, v143, 1
	v_add_u32_e32 v243, s0, v132
	v_add_u32_e32 v244, s0, v133
	v_add_u32_e32 v245, s0, v134
	v_add_u32_e32 v246, s0, v136
	v_add_u32_e32 v247, s0, v137
	v_readlane_b32 s0, v254, 38
	s_mov_b32 s88, 0
	v_cmp_gt_i32_e64 s[10:11], s1, v237
	s_ashr_i32 s91, s3, 31
	v_lshl_add_u64 v[206:207], s[50:51], 0, v[130:131]
	v_add_u32_e32 v242, 0, v135
	s_mov_b32 s26, s0
	v_readlane_b32 s0, v254, 36
	s_barrier
	v_readlane_b32 s1, v254, 37
	s_branch .LBB0_187

.LBB0_193:
	s_add_u32 s34, s34, s100
	s_addc_u32 s35, s35, 0
	s_add_u32 s1, s30, 0x100
	s_addc_u32 s4, s31, 0
	s_mov_b32 s30, 0
.LBB0_194:
	s_add_i32 s27, s30, 2
	s_add_u32 s33, s34, s100
	s_addc_u32 s31, s35, 0
	s_cmp_eq_u32 s90, s30
	s_cselect_b32 s31, s15, s31
	s_cselect_b32 s30, s14, s33
	s_cselect_b32 s45, s29, s4
	s_cselect_b32 s44, s28, s1
	s_add_i32 s33, 0, 0x14000
	v_add_u32_e32 v142, s62, v240
	v_add_u32_e32 v158, s33, v240
	ds_read_b128 v[130:133], v142
	ds_read_b128 v[134:137], v142 offset:1024
	ds_read_b128 v[138:141], v142 offset:2048
	ds_read_b128 v[142:145], v142 offset:3072
	ds_read_b128 v[146:149], v158
	ds_read_b128 v[150:153], v158 offset:1024
	ds_read_b128 v[154:157], v158 offset:2048
	ds_read_b128 v[158:161], v158 offset:3072
	v_lshl_add_u64 v[212:213], s[34:35], 0, v[204:205]
	s_add_i32 m0, s82, 0xc000
	ds_read_b128 v[162:165], v242
	ds_read_b128 v[166:169], v242 offset:1024
	ds_read_b128 v[170:173], v242 offset:2048
	ds_read_b128 v[174:177], v242 offset:3072
	ds_read_b128 v[178:181], v242 offset:4096
	ds_read_b128 v[182:185], v242 offset:5120
	ds_read_b128 v[186:189], v242 offset:6144
	ds_read_b128 v[208:211], v242 offset:7168
	global_load_lds_dwordx4 v[212:213], off
	v_lshl_add_u64 v[212:213], s[34:35], 0, v[206:207]
	s_add_i32 m0, s82, 0xe000
	s_nop 0
	global_load_lds_dwordx4 v[212:213], off
	s_waitcnt vmcnt(8)
	s_waitcnt lgkmcnt(0)
	s_barrier
	s_setprio 1
	s_waitcnt lgkmcnt(0)
	v_mfma_f32_16x16x32_bf16 v[126:129], v[130:133], v[162:165], v[126:129]
	v_mfma_f32_16x16x32_bf16 v[122:125], v[138:141], v[162:165], v[122:125]
	v_mfma_f32_16x16x32_bf16 v[110:113], v[130:133], v[170:173], v[110:113]
	v_mfma_f32_16x16x32_bf16 v[98:101], v[138:141], v[170:173], v[98:101]
	v_mfma_f32_16x16x32_bf16 v[94:97], v[130:133], v[178:181], v[94:97]
	v_mfma_f32_16x16x32_bf16 v[82:85], v[138:141], v[178:181], v[82:85]
	v_mfma_f32_16x16x32_bf16 v[78:81], v[130:133], v[186:189], v[78:81]
	v_mfma_f32_16x16x32_bf16 v[66:69], v[138:141], v[186:189], v[66:69]
	v_mfma_f32_16x16x32_bf16 v[126:129], v[134:137], v[166:169], v[126:129]
	v_mfma_f32_16x16x32_bf16 v[122:125], v[142:145], v[166:169], v[122:125]
	v_mfma_f32_16x16x32_bf16 v[110:113], v[134:137], v[174:177], v[110:113]
	v_mfma_f32_16x16x32_bf16 v[98:101], v[142:145], v[174:177], v[98:101]
	v_mfma_f32_16x16x32_bf16 v[94:97], v[134:137], v[182:185], v[94:97]
	v_mfma_f32_16x16x32_bf16 v[82:85], v[142:145], v[182:185], v[82:85]
	v_mfma_f32_16x16x32_bf16 v[78:81], v[134:137], v[208:211], v[78:81]
	v_mfma_f32_16x16x32_bf16 v[66:69], v[142:145], v[208:211], v[66:69]
	s_setprio 0
	s_setprio 1
	v_mfma_f32_16x16x32_bf16 v[118:121], v[146:149], v[162:165], v[118:121]
	v_mfma_f32_16x16x32_bf16 v[114:117], v[154:157], v[162:165], v[114:117]
	v_mfma_f32_16x16x32_bf16 v[106:109], v[146:149], v[170:173], v[106:109]
	v_mfma_f32_16x16x32_bf16 v[102:105], v[154:157], v[170:173], v[102:105]
	v_mfma_f32_16x16x32_bf16 v[90:93], v[146:149], v[178:181], v[90:93]
	v_mfma_f32_16x16x32_bf16 v[86:89], v[154:157], v[178:181], v[86:89]
	v_mfma_f32_16x16x32_bf16 v[74:77], v[146:149], v[186:189], v[74:77]
	v_mfma_f32_16x16x32_bf16 v[70:73], v[154:157], v[186:189], v[70:73]
	v_mfma_f32_16x16x32_bf16 v[118:121], v[150:153], v[166:169], v[118:121]
	v_mfma_f32_16x16x32_bf16 v[114:117], v[158:161], v[166:169], v[114:117]
	v_mfma_f32_16x16x32_bf16 v[106:109], v[150:153], v[174:177], v[106:109]
	v_mfma_f32_16x16x32_bf16 v[102:105], v[158:161], v[174:177], v[102:105]
	v_mfma_f32_16x16x32_bf16 v[90:93], v[150:153], v[182:185], v[90:93]
	v_mfma_f32_16x16x32_bf16 v[86:89], v[158:161], v[182:185], v[86:89]
	v_mfma_f32_16x16x32_bf16 v[74:77], v[150:153], v[208:211], v[74:77]
	v_mfma_f32_16x16x32_bf16 v[70:73], v[158:161], v[208:211], v[70:73]
	s_setprio 0
	s_barrier
	s_add_i32 s46, s62, s52
	v_lshl_add_u64 v[212:213], s[44:45], 0, v[48:49]
	s_mov_b32 m0, s46
	ds_read_b128 v[162:165], v242 offset:16384
	ds_read_b128 v[166:169], v242 offset:17408
	ds_read_b128 v[170:173], v242 offset:18432
	ds_read_b128 v[174:177], v242 offset:19456
	ds_read_b128 v[178:181], v242 offset:20480
	ds_read_b128 v[182:185], v242 offset:21504
	ds_read_b128 v[186:189], v242 offset:22528
	ds_read_b128 v[208:211], v242 offset:23552
	global_load_lds_dwordx4 v[212:213], off
	s_add_i32 m0, s46, 0x2000
	v_lshl_add_u64 v[214:215], s[44:45], 0, v[198:199]
	s_add_u32 s44, s44, s41
	s_addc_u32 s45, s45, 0
	s_add_i32 s33, s33, s52
	global_load_lds_dwordx4 v[214:215], off
	v_lshl_add_u64 v[216:217], s[44:45], 0, v[48:49]
	s_mov_b32 m0, s33
	v_lshl_add_u64 v[218:219], s[44:45], 0, v[198:199]
	global_load_lds_dwordx4 v[216:217], off
	s_add_i32 m0, s33, 0x2000
	v_lshl_add_u64 v[220:221], s[30:31], 0, v[202:203]
	global_load_lds_dwordx4 v[218:219], off
	s_mov_b32 m0, s82
	v_lshl_add_u64 v[222:223], s[30:31], 0, v[200:201]
	global_load_lds_dwordx4 v[220:221], off
	s_mov_b32 m0, s83
	s_nop 0
	global_load_lds_dwordx4 v[222:223], off
	s_waitcnt vmcnt(8)
	s_waitcnt lgkmcnt(0)
	s_barrier
	s_setprio 1
	s_waitcnt lgkmcnt(0)
	v_mfma_f32_16x16x32_bf16 v[62:65], v[130:133], v[162:165], v[62:65]
	v_mfma_f32_16x16x32_bf16 v[50:53], v[138:141], v[162:165], v[50:53]
	v_mfma_f32_16x16x32_bf16 v[44:47], v[130:133], v[170:173], v[44:47]
	v_mfma_f32_16x16x32_bf16 v[32:35], v[138:141], v[170:173], v[32:35]
	v_mfma_f32_16x16x32_bf16 v[28:31], v[130:133], v[178:181], v[28:31]
	v_mfma_f32_16x16x32_bf16 v[16:19], v[138:141], v[178:181], v[16:19]
	v_mfma_f32_16x16x32_bf16 v[12:15], v[130:133], v[186:189], v[12:15]
	v_mfma_f32_16x16x32_bf16 v[0:3], v[138:141], v[186:189], v[0:3]
	v_mfma_f32_16x16x32_bf16 v[62:65], v[134:137], v[166:169], v[62:65]
	v_mfma_f32_16x16x32_bf16 v[50:53], v[142:145], v[166:169], v[50:53]
	v_mfma_f32_16x16x32_bf16 v[44:47], v[134:137], v[174:177], v[44:47]
	v_mfma_f32_16x16x32_bf16 v[32:35], v[142:145], v[174:177], v[32:35]
	v_mfma_f32_16x16x32_bf16 v[28:31], v[134:137], v[182:185], v[28:31]
	v_mfma_f32_16x16x32_bf16 v[16:19], v[142:145], v[182:185], v[16:19]
	v_mfma_f32_16x16x32_bf16 v[12:15], v[134:137], v[208:211], v[12:15]
	v_mfma_f32_16x16x32_bf16 v[0:3], v[142:145], v[208:211], v[0:3]
	s_setprio 0
	s_setprio 1
	v_mfma_f32_16x16x32_bf16 v[58:61], v[146:149], v[162:165], v[58:61]
	v_mfma_f32_16x16x32_bf16 v[54:57], v[154:157], v[162:165], v[54:57]
	v_mfma_f32_16x16x32_bf16 v[40:43], v[146:149], v[170:173], v[40:43]
	v_mfma_f32_16x16x32_bf16 v[36:39], v[154:157], v[170:173], v[36:39]
	v_mfma_f32_16x16x32_bf16 v[24:27], v[146:149], v[178:181], v[24:27]
	v_mfma_f32_16x16x32_bf16 v[20:23], v[154:157], v[178:181], v[20:23]
	v_mfma_f32_16x16x32_bf16 v[8:11], v[146:149], v[186:189], v[8:11]
	v_mfma_f32_16x16x32_bf16 v[4:7], v[154:157], v[186:189], v[4:7]
	v_mfma_f32_16x16x32_bf16 v[58:61], v[150:153], v[166:169], v[58:61]
	v_mfma_f32_16x16x32_bf16 v[54:57], v[158:161], v[166:169], v[54:57]
	v_mfma_f32_16x16x32_bf16 v[40:43], v[150:153], v[174:177], v[40:43]
	v_mfma_f32_16x16x32_bf16 v[36:39], v[158:161], v[174:177], v[36:39]
	v_mfma_f32_16x16x32_bf16 v[24:27], v[150:153], v[182:185], v[24:27]
	v_mfma_f32_16x16x32_bf16 v[20:23], v[158:161], v[182:185], v[20:23]
	v_mfma_f32_16x16x32_bf16 v[8:11], v[150:153], v[208:211], v[8:11]
	v_mfma_f32_16x16x32_bf16 v[4:7], v[158:161], v[208:211], v[4:7]
	s_setprio 0
	s_barrier
	s_add_i32 s33, 0, 0x18000
	s_add_i32 s44, 0, 0x1c000
	v_add_u32_e32 v142, s33, v240
	v_add_u32_e32 v158, s44, v240
	ds_read_b128 v[130:133], v142
	ds_read_b128 v[134:137], v142 offset:1024
	ds_read_b128 v[138:141], v142 offset:2048
	ds_read_b128 v[142:145], v142 offset:3072
	ds_read_b128 v[146:149], v158
	ds_read_b128 v[150:153], v158 offset:1024
	ds_read_b128 v[154:157], v158 offset:2048
	ds_read_b128 v[158:161], v158 offset:3072
	s_add_u32 s30, s30, s50
	s_addc_u32 s31, s31, 0
	s_mov_b32 m0, s84
	v_lshl_add_u64 v[224:225], s[30:31], 0, v[202:203]
	ds_read_b128 v[162:165], v242 offset:32768
	ds_read_b128 v[166:169], v242 offset:33792
	ds_read_b128 v[170:173], v242 offset:34816
	ds_read_b128 v[174:177], v242 offset:35840
	ds_read_b128 v[178:181], v242 offset:36864
	ds_read_b128 v[182:185], v242 offset:37888
	ds_read_b128 v[186:189], v242 offset:38912
	ds_read_b128 v[208:211], v242 offset:39936
	global_load_lds_dwordx4 v[224:225], off
	v_lshl_add_u64 v[224:225], s[30:31], 0, v[200:201]
	s_mov_b32 m0, s85
	s_nop 0
	global_load_lds_dwordx4 v[224:225], off
	s_waitcnt vmcnt(8)
	s_waitcnt lgkmcnt(0)
	s_barrier
	s_setprio 1
	s_waitcnt lgkmcnt(0)
	v_mfma_f32_16x16x32_bf16 v[126:129], v[130:133], v[162:165], v[126:129]
	v_mfma_f32_16x16x32_bf16 v[122:125], v[138:141], v[162:165], v[122:125]
	v_mfma_f32_16x16x32_bf16 v[110:113], v[130:133], v[170:173], v[110:113]
	v_mfma_f32_16x16x32_bf16 v[98:101], v[138:141], v[170:173], v[98:101]
	v_mfma_f32_16x16x32_bf16 v[94:97], v[130:133], v[178:181], v[94:97]
	v_mfma_f32_16x16x32_bf16 v[82:85], v[138:141], v[178:181], v[82:85]
	v_mfma_f32_16x16x32_bf16 v[78:81], v[130:133], v[186:189], v[78:81]
	v_mfma_f32_16x16x32_bf16 v[66:69], v[138:141], v[186:189], v[66:69]
	v_mfma_f32_16x16x32_bf16 v[126:129], v[134:137], v[166:169], v[126:129]
	v_mfma_f32_16x16x32_bf16 v[122:125], v[142:145], v[166:169], v[122:125]
	v_mfma_f32_16x16x32_bf16 v[110:113], v[134:137], v[174:177], v[110:113]
	v_mfma_f32_16x16x32_bf16 v[98:101], v[142:145], v[174:177], v[98:101]
	v_mfma_f32_16x16x32_bf16 v[94:97], v[134:137], v[182:185], v[94:97]
	v_mfma_f32_16x16x32_bf16 v[82:85], v[142:145], v[182:185], v[82:85]
	v_mfma_f32_16x16x32_bf16 v[78:81], v[134:137], v[208:211], v[78:81]
	v_mfma_f32_16x16x32_bf16 v[66:69], v[142:145], v[208:211], v[66:69]
	s_setprio 0
	s_setprio 1
	v_mfma_f32_16x16x32_bf16 v[118:121], v[146:149], v[162:165], v[118:121]
	v_mfma_f32_16x16x32_bf16 v[114:117], v[154:157], v[162:165], v[114:117]
	v_mfma_f32_16x16x32_bf16 v[106:109], v[146:149], v[170:173], v[106:109]
	v_mfma_f32_16x16x32_bf16 v[102:105], v[154:157], v[170:173], v[102:105]
	v_mfma_f32_16x16x32_bf16 v[90:93], v[146:149], v[178:181], v[90:93]
	v_mfma_f32_16x16x32_bf16 v[86:89], v[154:157], v[178:181], v[86:89]
	v_mfma_f32_16x16x32_bf16 v[74:77], v[146:149], v[186:189], v[74:77]
	v_mfma_f32_16x16x32_bf16 v[70:73], v[154:157], v[186:189], v[70:73]
	v_mfma_f32_16x16x32_bf16 v[118:121], v[150:153], v[166:169], v[118:121]
	v_mfma_f32_16x16x32_bf16 v[114:117], v[158:161], v[166:169], v[114:117]
	v_mfma_f32_16x16x32_bf16 v[106:109], v[150:153], v[174:177], v[106:109]
	v_mfma_f32_16x16x32_bf16 v[102:105], v[158:161], v[174:177], v[102:105]
	v_mfma_f32_16x16x32_bf16 v[90:93], v[150:153], v[182:185], v[90:93]
	v_mfma_f32_16x16x32_bf16 v[86:89], v[158:161], v[182:185], v[86:89]
	v_mfma_f32_16x16x32_bf16 v[74:77], v[150:153], v[208:211], v[74:77]
	v_mfma_f32_16x16x32_bf16 v[70:73], v[158:161], v[208:211], v[70:73]
	s_setprio 0
	s_barrier
	s_add_i32 s30, s33, s52
	v_lshl_add_u64 v[212:213], v[212:213], 0, s[70:71]
	s_mov_b32 m0, s30
	ds_read_b128 v[162:165], v242 offset:49152
	ds_read_b128 v[166:169], v242 offset:50176
	ds_read_b128 v[170:173], v242 offset:51200
	ds_read_b128 v[174:177], v242 offset:52224
	ds_read_b128 v[178:181], v242 offset:53248
	ds_read_b128 v[182:185], v242 offset:54272
	ds_read_b128 v[186:189], v242 offset:55296
	ds_read_b128 v[208:211], v242 offset:56320
	global_load_lds_dwordx4 v[212:213], off
	v_lshl_add_u64 v[212:213], v[214:215], 0, s[70:71]
	s_add_i32 m0, s30, 0x2000
	s_add_i32 s30, s44, s52
	global_load_lds_dwordx4 v[212:213], off
	v_lshl_add_u64 v[212:213], v[216:217], 0, s[70:71]
	s_mov_b32 m0, s30
	s_nop 0
	global_load_lds_dwordx4 v[212:213], off
	v_lshl_add_u64 v[212:213], v[218:219], 0, s[70:71]
	s_add_i32 m0, s30, 0x2000
	s_nop 0
	global_load_lds_dwordx4 v[212:213], off
	v_lshl_add_u64 v[212:213], v[220:221], 0, s[100:101]
	s_mov_b32 m0, s86
	s_nop 0
	global_load_lds_dwordx4 v[212:213], off
	v_lshl_add_u64 v[212:213], v[222:223], 0, s[100:101]
	s_mov_b32 m0, s87
	s_nop 0
	global_load_lds_dwordx4 v[212:213], off
	s_waitcnt vmcnt(8)
	s_waitcnt lgkmcnt(0)
	s_barrier
	s_setprio 1
	s_waitcnt lgkmcnt(0)
	v_mfma_f32_16x16x32_bf16 v[62:65], v[130:133], v[162:165], v[62:65]
	v_mfma_f32_16x16x32_bf16 v[50:53], v[138:141], v[162:165], v[50:53]
	v_mfma_f32_16x16x32_bf16 v[44:47], v[130:133], v[170:173], v[44:47]
	v_mfma_f32_16x16x32_bf16 v[32:35], v[138:141], v[170:173], v[32:35]
	v_mfma_f32_16x16x32_bf16 v[28:31], v[130:133], v[178:181], v[28:31]
	v_mfma_f32_16x16x32_bf16 v[16:19], v[138:141], v[178:181], v[16:19]
	v_mfma_f32_16x16x32_bf16 v[12:15], v[130:133], v[186:189], v[12:15]
	v_mfma_f32_16x16x32_bf16 v[0:3], v[138:141], v[186:189], v[0:3]
	v_mfma_f32_16x16x32_bf16 v[62:65], v[134:137], v[166:169], v[62:65]
	v_mfma_f32_16x16x32_bf16 v[50:53], v[142:145], v[166:169], v[50:53]
	v_mfma_f32_16x16x32_bf16 v[44:47], v[134:137], v[174:177], v[44:47]
	v_mfma_f32_16x16x32_bf16 v[32:35], v[142:145], v[174:177], v[32:35]
	v_mfma_f32_16x16x32_bf16 v[28:31], v[134:137], v[182:185], v[28:31]
	v_mfma_f32_16x16x32_bf16 v[16:19], v[142:145], v[182:185], v[16:19]
	v_mfma_f32_16x16x32_bf16 v[12:15], v[134:137], v[208:211], v[12:15]
	v_mfma_f32_16x16x32_bf16 v[0:3], v[142:145], v[208:211], v[0:3]
	s_setprio 0
	s_setprio 1
	v_mfma_f32_16x16x32_bf16 v[58:61], v[146:149], v[162:165], v[58:61]
	v_mfma_f32_16x16x32_bf16 v[54:57], v[154:157], v[162:165], v[54:57]
	v_mfma_f32_16x16x32_bf16 v[40:43], v[146:149], v[170:173], v[40:43]
	v_mfma_f32_16x16x32_bf16 v[36:39], v[154:157], v[170:173], v[36:39]
	v_mfma_f32_16x16x32_bf16 v[24:27], v[146:149], v[178:181], v[24:27]
	v_mfma_f32_16x16x32_bf16 v[20:23], v[154:157], v[178:181], v[20:23]
	v_mfma_f32_16x16x32_bf16 v[8:11], v[146:149], v[186:189], v[8:11]
	v_mfma_f32_16x16x32_bf16 v[4:7], v[154:157], v[186:189], v[4:7]
	v_mfma_f32_16x16x32_bf16 v[58:61], v[150:153], v[166:169], v[58:61]
	v_mfma_f32_16x16x32_bf16 v[54:57], v[158:161], v[166:169], v[54:57]
	v_mfma_f32_16x16x32_bf16 v[40:43], v[150:153], v[174:177], v[40:43]
	v_mfma_f32_16x16x32_bf16 v[36:39], v[158:161], v[174:177], v[36:39]
	v_mfma_f32_16x16x32_bf16 v[24:27], v[150:153], v[182:185], v[24:27]
	v_mfma_f32_16x16x32_bf16 v[20:23], v[158:161], v[182:185], v[20:23]
	v_mfma_f32_16x16x32_bf16 v[8:11], v[150:153], v[208:211], v[8:11]
	v_mfma_f32_16x16x32_bf16 v[4:7], v[158:161], v[208:211], v[4:7]
	s_setprio 0
	s_barrier
	s_add_u32 s34, s34, s100
	s_addc_u32 s35, s35, 0
	s_add_u32 s34, s34, s100
	s_addc_u32 s35, s35, 0
	s_add_u32 s1, s1, 0x100
	s_addc_u32 s4, s4, 0
	s_cmp_ge_u32 s27, s89
	s_mov_b32 s30, s27
	s_cbranch_scc0 .LBB0_194
	s_and_b64 vcc, exec, s[24:25]
	s_cbranch_vccz .LBB0_197
	s_barrier

.LBB0_206:
	s_andn2_b64 vcc, exec, s[14:15]
	s_cbranch_vccnz .LBB0_227
	s_and_b64 vcc, exec, s[6:7]
	v_readfirstlane_b32 s0, v237
	s_cbranch_vccnz .LBB0_227
	v_lshlrev_b32_e32 v0, 4, v237
	v_add_u32_e32 v1, 0x2000, v0
	v_ashrrev_i32_e32 v2, 31, v1
	v_lshrrev_b32_e32 v2, 22, v2
	v_add_u32_e32 v2, v1, v2
	v_ashrrev_i32_e32 v2, 10, v2
	v_mul_i32_i24_e32 v3, 0x400, v2
	v_sub_u32_e32 v1, v1, v3
	v_lshrrev_b32_e32 v3, 4, v1
	v_bitop3_b32 v1, v3, v1, 32 bitop3:0x6c
	v_ashrrev_i32_e32 v3, 31, v1
	v_lshrrev_b32_e32 v3, 26, v3
	v_add_u32_e32 v3, v1, v3
	v_lshlrev_b32_e32 v5, 3, v2
	v_ashrrev_i32_e32 v4, 6, v3
	v_and_b32_e32 v5, -16, v5
	v_lshlrev_b32_e32 v2, 5, v2
	v_add_u32_e32 v5, v4, v5
	v_and_b32_e32 v138, 32, v2
	v_and_b32_e32 v2, 0xc0, v3
	v_and_b32_e32 v4, 3, v4
	s_mov_b32 s6, 0xffffe0
	v_lshrrev_b32_e32 v6, 2, v5
	v_lshlrev_b32_e32 v7, 1, v5
	v_sub_u32_e32 v1, v1, v2
	v_and_or_b32 v4, v5, s6, v4
	v_and_b32_e32 v6, 4, v6
	v_and_b32_e32 v7, 24, v7
	v_ashrrev_i16_sdwa v1, v227, sext(v1) dst_sel:DWORD dst_unused:UNUSED_PAD src0_sel:DWORD src1_sel:BYTE_0
	v_or3_b32 v4, v4, v6, v7
	v_bfe_i32 v139, v1, 0, 16
	v_mul_u32_u24_e32 v4, 0xb00, v4
	v_add_u32_e32 v1, v138, v139
	v_lshlrev_b32_e32 v140, 6, v5
	v_add_lshl_u32 v198, v4, v1, 1
	v_add_lshl_u32 v200, v1, v140, 1
	v_bfe_i32 v1, v237, 27, 1
	v_lshrrev_b32_e32 v1, 22, v1
	v_add_u32_e32 v1, v0, v1
	v_and_b32_e32 v1, 0xfffffc00, v1
	v_sub_u32_e32 v0, v0, v1
	v_lshrrev_b32_e32 v1, 4, v0
	v_ashrrev_i32_e32 v3, 31, v237
	v_bitop3_b32 v0, v1, v0, 32 bitop3:0x6c
	v_lshrrev_b32_e32 v3, 26, v3
	v_ashrrev_i32_e32 v1, 31, v0
	v_add_u32_e32 v3, v237, v3
	v_lshrrev_b32_e32 v1, 26, v1
	v_ashrrev_i32_e32 v3, 6, v3
	v_add_u32_e32 v1, v0, v1
	v_lshlrev_b32_e32 v4, 3, v3
	v_ashrrev_i32_e32 v2, 6, v1
	v_and_b32_e32 v4, -16, v4
	v_add_u32_e32 v4, v2, v4
	v_and_b32_e32 v2, 3, v2
	v_and_or_b32 v2, v4, s6, v2
	v_readlane_b32 s6, v254, 36
	s_lshl_b32 s28, s40, 9
	v_and_b32_e32 v1, 0xc0, v1
	v_readlane_b32 s7, v254, 37
	s_mov_b32 s8, s6
	s_ashr_i32 s4, s0, 6
	v_lshrrev_b32_e32 v5, 2, v4
	v_lshlrev_b32_e32 v6, 1, v4
	v_sub_u32_e32 v0, v0, v1
	s_mul_i32 s7, s28, s8
	v_readlane_b32 s8, v254, 38
	s_ashr_i32 s1, s0, 8
	s_movk_i32 s50, 0x4000
	s_mov_b32 s100, 0x8000
	s_mov_b32 s101, 0
	s_lshl_b32 s29, s4, 10
	v_and_b32_e32 v5, 4, v5
	v_and_b32_e32 v6, 24, v6
	v_lshlrev_b32_e32 v3, 5, v3
	v_ashrrev_i16_sdwa v0, v227, sext(v0) dst_sel:DWORD dst_unused:UNUSED_PAD src0_sel:DWORD src1_sel:BYTE_0
	s_mul_i32 s8, s8, 0x160000
	v_or3_b32 v2, v2, v5, v6
	v_and_b32_e32 v141, 32, v3
	v_bfe_i32 v142, v0, 0, 16
	s_add_u32 s22, s38, s8
	v_mul_u32_u24_e32 v2, 0xb00, v2
	v_add_u32_e32 v0, v141, v142
	s_addc_u32 s23, s39, 0
	s_add_i32 s30, s29, 0
	v_add_lshl_u32 v48, v2, v0, 1
	v_lshlrev_b32_e32 v143, 6, v4
	s_add_i32 m0, s30, 0x10000
	s_load_dwordx2 s[10:11], s[80:81], 0x88
	v_add_lshl_u32 v202, v0, v143, 1
	v_mov_b64 v[126:127], 0
	v_mov_b64 v[128:129], 0
	v_mov_b64 v[122:123], 0
	v_mov_b64 v[124:125], 0
	v_mov_b64 v[110:111], 0
	v_mov_b64 v[112:113], 0
	v_mov_b64 v[102:103], 0
	v_mov_b64 v[104:105], 0
	v_mov_b64 v[94:95], 0
	v_mov_b64 v[96:97], 0
	v_mov_b64 v[86:87], 0
	v_mov_b64 v[88:89], 0
	v_mov_b64 v[78:79], 0
	v_mov_b64 v[80:81], 0
	v_mov_b64 v[70:71], 0
	v_mov_b64 v[72:73], 0
	v_mov_b64 v[118:119], 0
	v_mov_b64 v[120:121], 0
	v_mov_b64 v[114:115], 0
	v_mov_b64 v[116:117], 0
	v_mov_b64 v[106:107], 0
	v_mov_b64 v[108:109], 0
	v_mov_b64 v[98:99], 0
	v_mov_b64 v[100:101], 0
	v_mov_b64 v[90:91], 0
	v_mov_b64 v[92:93], 0
	v_mov_b64 v[82:83], 0
	v_mov_b64 v[84:85], 0
	v_mov_b64 v[74:75], 0
	v_mov_b64 v[76:77], 0
	v_mov_b64 v[66:67], 0
	v_mov_b64 v[68:69], 0
	v_mov_b64 v[62:63], 0
	v_mov_b64 v[64:65], 0
	v_mov_b64 v[54:55], 0
	v_mov_b64 v[56:57], 0
	v_mov_b64 v[44:45], 0
	v_mov_b64 v[46:47], 0
	v_mov_b64 v[36:37], 0
	v_mov_b64 v[38:39], 0
	v_mov_b64 v[28:29], 0
	v_mov_b64 v[30:31], 0
	v_mov_b64 v[20:21], 0
	v_mov_b64 v[22:23], 0
	s_waitcnt lgkmcnt(0)
	v_mov_b64 v[12:13], 0
	v_mov_b64 v[14:15], 0
	v_mov_b64 v[0:1], 0
	v_mov_b64 v[2:3], 0
	v_mov_b64 v[58:59], 0
	v_mov_b64 v[60:61], 0
	v_mov_b64 v[50:51], 0
	v_mov_b64 v[52:53], 0
	v_mov_b64 v[40:41], 0
	v_mov_b64 v[42:43], 0
	v_mov_b64 v[32:33], 0
	v_mov_b64 v[34:35], 0
	v_mov_b64 v[24:25], 0
	v_mov_b64 v[26:27], 0
	v_mov_b64 v[16:17], 0
	v_mov_b64 v[18:19], 0
	v_mov_b64 v[8:9], 0
	v_mov_b64 v[10:11], 0
	v_mov_b64 v[4:5], 0
	v_mov_b64 v[6:7], 0
	global_load_lds_dwordx4 v48, s[22:23]
	s_add_i32 m0, s30, 0x12000
	s_mul_hi_i32 s6, s28, s6
	s_add_u32 s20, s36, s7
	s_addc_u32 s21, s37, s6
	s_add_u32 s6, s22, 0xb0000
	global_load_lds_dwordx4 v198, s[22:23]
	s_addc_u32 s7, s23, 0
	s_add_i32 m0, s30, 0x14000
	s_add_i32 s31, s30, 0x2000
	global_load_lds_dwordx4 v48, s[6:7]
	s_add_i32 m0, s30, 0x16000
	v_mov_b32_e32 v199, v49
	global_load_lds_dwordx4 v198, s[6:7]
	s_mov_b32 m0, s30
	s_add_u32 s6, s20, s50
	global_load_lds_dwordx4 v202, s[20:21]
	s_mov_b32 m0, s31
	s_addc_u32 s7, s21, 0
	s_add_i32 s34, s30, 0x4000
	global_load_lds_dwordx4 v200, s[20:21]
	s_mov_b32 m0, s34
	s_add_i32 s35, s30, 0x6000
	global_load_lds_dwordx4 v202, s[6:7]
	s_mov_b32 m0, s35
	v_mov_b32_e32 v203, v49
	global_load_lds_dwordx4 v200, s[6:7]
	v_mov_b32_e32 v201, v49
	s_cmp_eq_u32 s1, 1
	v_lshl_add_u64 v[136:137], s[22:23], 0, v[48:49]
	v_lshl_add_u64 v[134:135], s[22:23], 0, v[198:199]
	v_lshl_add_u64 v[130:131], s[20:21], 0, v[202:203]
	s_cselect_b64 s[12:13], -1, 0
	s_cmp_lg_u32 s1, 1
	v_lshl_add_u64 v[132:133], s[20:21], 0, v[200:201]
	s_cbranch_scc1 .LBB0_210
	s_barrier
.LBB0_210:
	s_lshl_b32 s4, s4, 5
	s_and_b32 s4, s4, 0x60
	s_add_i32 m0, s30, 0x18000
	v_lshl_add_u64 v[136:137], v[136:137], 0, s[70:71]
	s_lshl_b32 s8, s1, 13
	s_lshl_b32 s9, s4, 7
	s_waitcnt vmcnt(2)
	s_barrier
	global_load_lds_dwordx4 v[136:137], off
	v_lshl_add_u64 v[134:135], v[134:135], 0, s[70:71]
	s_add_i32 m0, s30, 0x1a000
	s_add_i32 s40, s30, 0x8000
	s_add_i32 s41, s30, 0xa000
	global_load_lds_dwordx4 v[134:135], off
	v_lshl_add_u64 v[130:131], v[130:131], 0, s[100:101]
	s_mov_b32 m0, s40
	s_add_u32 s6, s22, 0xb0080
	global_load_lds_dwordx4 v[130:131], off
	v_lshl_add_u64 v[130:131], v[132:133], 0, s[100:101]
	s_mov_b32 m0, s41
	s_addc_u32 s7, s23, 0
	global_load_lds_dwordx4 v[130:131], off
	s_add_i32 m0, s30, 0x1c000
	v_lshl_add_u64 v[130:131], s[6:7], 0, v[48:49]
	global_load_lds_dwordx4 v[130:131], off
	v_lshl_add_u64 v[130:131], s[6:7], 0, v[198:199]
	s_add_i32 m0, s30, 0x1e000
	s_cmpk_lt_u32 s0, 0x100
	global_load_lds_dwordx4 v[130:131], off
	v_lshrrev_b32_e32 v131, 1, v237
	v_and_b32_e32 v131, 24, v131
	v_and_b32_e32 v130, 15, v237
	v_lshlrev_b32_e32 v132, 1, v131
	v_lshl_or_b32 v238, s1, 6, v130
	v_lshl_or_b32 v130, v130, 6, v132
	v_lshlrev_b32_e32 v132, 2, v237
	v_and_b32_e32 v132, 32, v132
	v_bitop3_b32 v133, v130, s8, v132 bitop3:0xde
	v_bitop3_b32 v239, s9, v130, v132 bitop3:0xf6
	v_add_u32_e32 v130, v143, v141
	v_or_b32_e32 v240, s4, v131
	v_add_lshl_u32 v130, v130, v142, 1
	v_mov_b32_e32 v131, v49
	s_waitcnt vmcnt(6)
	v_lshl_add_u64 v[204:205], s[50:51], 0, v[130:131]
	v_add_u32_e32 v130, v140, v138
	v_add_lshl_u32 v130, v130, v139, 1
	v_readlane_b32 s6, v254, 36
	s_cselect_b64 s[14:15], -1, 0
	s_ashr_i32 s48, s3, 31
	v_lshl_add_u64 v[206:207], s[50:51], 0, v[130:131]
	s_mov_b32 s49, 0
	v_add_u32_e32 v241, 0, v133
	v_readlane_b32 s0, v254, 38
	s_mov_b32 s1, s6
	s_barrier
	v_readlane_b32 s7, v254, 37
	s_branch .LBB0_213

.LBB0_219:
	s_add_u32 s4, s22, 0x100
	s_addc_u32 s33, s23, 0
	s_add_u32 s22, s20, 0x8000
	s_addc_u32 s23, s21, 0
	v_lshl_add_u64 v[130:131], s[22:23], 0, v[204:205]
	v_lshl_add_u64 v[132:133], s[22:23], 0, v[206:207]
	s_mov_b32 s44, -2
	s_mov_b64 s[22:23], 0
.LBB0_220:
	s_lshl_b64 s[100:101], s[22:23], 8
	s_add_u32 s24, s20, s100
	s_addc_u32 s25, s21, s101
	s_add_u32 s24, s24, 0x10000
	s_addc_u32 s25, s25, 0
	s_add_u32 s45, s4, s22
	s_addc_u32 s46, s33, s23
	s_cmpk_eq_i32 s22, 0x1500
	s_cselect_b32 s27, s9, s25
	s_cselect_b32 s26, s8, s24
	s_cselect_b32 s25, s19, s46
	s_cselect_b32 s24, s18, s45
	s_add_i32 s45, 0, 0x14000
	v_add_u32_e32 v146, s62, v239
	v_add_u32_e32 v162, s45, v239
	ds_read_b128 v[134:137], v146
	ds_read_b128 v[138:141], v146 offset:1024
	ds_read_b128 v[142:145], v146 offset:2048
	ds_read_b128 v[146:149], v146 offset:3072
	ds_read_b128 v[150:153], v162
	ds_read_b128 v[154:157], v162 offset:1024
	ds_read_b128 v[158:161], v162 offset:2048
	ds_read_b128 v[162:165], v162 offset:3072
	v_lshl_add_u64 v[216:217], v[130:131], 0, s[100:101]
	s_add_i32 m0, s30, 0xc000
	ds_read_b128 v[166:169], v241
	ds_read_b128 v[170:173], v241 offset:1024
	ds_read_b128 v[174:177], v241 offset:2048
	ds_read_b128 v[178:181], v241 offset:3072
	ds_read_b128 v[182:185], v241 offset:4096
	ds_read_b128 v[186:189], v241 offset:5120
	ds_read_b128 v[208:211], v241 offset:6144
	ds_read_b128 v[212:215], v241 offset:7168
	global_load_lds_dwordx4 v[216:217], off
	v_lshl_add_u64 v[216:217], v[132:133], 0, s[100:101]
	s_add_i32 m0, s30, 0xe000
	s_nop 0
	global_load_lds_dwordx4 v[216:217], off
	s_waitcnt vmcnt(8)
	s_waitcnt lgkmcnt(0)
	s_barrier
	s_setprio 1
	s_waitcnt lgkmcnt(0)
	v_mfma_f32_16x16x32_bf16 v[126:129], v[134:137], v[166:169], v[126:129]
	v_mfma_f32_16x16x32_bf16 v[122:125], v[142:145], v[166:169], v[122:125]
	v_mfma_f32_16x16x32_bf16 v[110:113], v[134:137], v[174:177], v[110:113]
	v_mfma_f32_16x16x32_bf16 v[102:105], v[142:145], v[174:177], v[102:105]
	v_mfma_f32_16x16x32_bf16 v[94:97], v[134:137], v[182:185], v[94:97]
	v_mfma_f32_16x16x32_bf16 v[86:89], v[142:145], v[182:185], v[86:89]
	v_mfma_f32_16x16x32_bf16 v[78:81], v[134:137], v[208:211], v[78:81]
	v_mfma_f32_16x16x32_bf16 v[70:73], v[142:145], v[208:211], v[70:73]
	v_mfma_f32_16x16x32_bf16 v[126:129], v[138:141], v[170:173], v[126:129]
	v_mfma_f32_16x16x32_bf16 v[122:125], v[146:149], v[170:173], v[122:125]
	v_mfma_f32_16x16x32_bf16 v[110:113], v[138:141], v[178:181], v[110:113]
	v_mfma_f32_16x16x32_bf16 v[102:105], v[146:149], v[178:181], v[102:105]
	v_mfma_f32_16x16x32_bf16 v[94:97], v[138:141], v[186:189], v[94:97]
	v_mfma_f32_16x16x32_bf16 v[86:89], v[146:149], v[186:189], v[86:89]
	v_mfma_f32_16x16x32_bf16 v[78:81], v[138:141], v[212:215], v[78:81]
	v_mfma_f32_16x16x32_bf16 v[70:73], v[146:149], v[212:215], v[70:73]
	s_setprio 0
	s_setprio 1
	v_mfma_f32_16x16x32_bf16 v[118:121], v[150:153], v[166:169], v[118:121]
	v_mfma_f32_16x16x32_bf16 v[114:117], v[158:161], v[166:169], v[114:117]
	v_mfma_f32_16x16x32_bf16 v[106:109], v[150:153], v[174:177], v[106:109]
	v_mfma_f32_16x16x32_bf16 v[98:101], v[158:161], v[174:177], v[98:101]
	v_mfma_f32_16x16x32_bf16 v[90:93], v[150:153], v[182:185], v[90:93]
	v_mfma_f32_16x16x32_bf16 v[82:85], v[158:161], v[182:185], v[82:85]
	v_mfma_f32_16x16x32_bf16 v[74:77], v[150:153], v[208:211], v[74:77]
	v_mfma_f32_16x16x32_bf16 v[66:69], v[158:161], v[208:211], v[66:69]
	v_mfma_f32_16x16x32_bf16 v[118:121], v[154:157], v[170:173], v[118:121]
	v_mfma_f32_16x16x32_bf16 v[114:117], v[162:165], v[170:173], v[114:117]
	v_mfma_f32_16x16x32_bf16 v[106:109], v[154:157], v[178:181], v[106:109]
	v_mfma_f32_16x16x32_bf16 v[98:101], v[162:165], v[178:181], v[98:101]
	v_mfma_f32_16x16x32_bf16 v[90:93], v[154:157], v[186:189], v[90:93]
	v_mfma_f32_16x16x32_bf16 v[82:85], v[162:165], v[186:189], v[82:85]
	v_mfma_f32_16x16x32_bf16 v[74:77], v[154:157], v[212:215], v[74:77]
	v_mfma_f32_16x16x32_bf16 v[66:69], v[162:165], v[212:215], v[66:69]
	s_setprio 0
	s_barrier
	s_add_i32 s46, s62, s29
	v_lshl_add_u64 v[216:217], s[24:25], 0, v[48:49]
	s_mov_b32 m0, s46
	ds_read_b128 v[166:169], v241 offset:16384
	ds_read_b128 v[170:173], v241 offset:17408
	ds_read_b128 v[174:177], v241 offset:18432
	ds_read_b128 v[178:181], v241 offset:19456
	ds_read_b128 v[182:185], v241 offset:20480
	ds_read_b128 v[186:189], v241 offset:21504
	ds_read_b128 v[208:211], v241 offset:22528
	ds_read_b128 v[212:215], v241 offset:23552
	global_load_lds_dwordx4 v[216:217], off
	s_add_i32 m0, s46, 0x2000
	s_add_u32 s54, s24, 0xb0000
	v_lshl_add_u64 v[218:219], s[24:25], 0, v[198:199]
	s_addc_u32 s55, s25, 0
	s_add_i32 s45, s45, s29
	global_load_lds_dwordx4 v[218:219], off
	v_lshl_add_u64 v[220:221], s[54:55], 0, v[48:49]
	s_mov_b32 m0, s45
	v_lshl_add_u64 v[222:223], s[26:27], 0, v[200:201]
	global_load_lds_dwordx4 v[220:221], off
	v_lshl_add_u64 v[220:221], s[54:55], 0, v[198:199]
	s_add_i32 m0, s45, 0x2000
	s_nop 0
	global_load_lds_dwordx4 v[220:221], off
	v_lshl_add_u64 v[220:221], s[26:27], 0, v[202:203]
	s_mov_b32 m0, s30
	s_nop 0
	global_load_lds_dwordx4 v[220:221], off
	s_mov_b32 m0, s31
	s_nop 0
	global_load_lds_dwordx4 v[222:223], off
	s_waitcnt vmcnt(8)
	s_waitcnt lgkmcnt(0)
	s_barrier
	s_setprio 1
	s_waitcnt lgkmcnt(0)
	v_mfma_f32_16x16x32_bf16 v[62:65], v[134:137], v[166:169], v[62:65]
	v_mfma_f32_16x16x32_bf16 v[54:57], v[142:145], v[166:169], v[54:57]
	v_mfma_f32_16x16x32_bf16 v[44:47], v[134:137], v[174:177], v[44:47]
	v_mfma_f32_16x16x32_bf16 v[36:39], v[142:145], v[174:177], v[36:39]
	v_mfma_f32_16x16x32_bf16 v[28:31], v[134:137], v[182:185], v[28:31]
	v_mfma_f32_16x16x32_bf16 v[20:23], v[142:145], v[182:185], v[20:23]
	v_mfma_f32_16x16x32_bf16 v[12:15], v[134:137], v[208:211], v[12:15]
	v_mfma_f32_16x16x32_bf16 v[0:3], v[142:145], v[208:211], v[0:3]
	v_mfma_f32_16x16x32_bf16 v[62:65], v[138:141], v[170:173], v[62:65]
	v_mfma_f32_16x16x32_bf16 v[54:57], v[146:149], v[170:173], v[54:57]
	v_mfma_f32_16x16x32_bf16 v[44:47], v[138:141], v[178:181], v[44:47]
	v_mfma_f32_16x16x32_bf16 v[36:39], v[146:149], v[178:181], v[36:39]
	v_mfma_f32_16x16x32_bf16 v[28:31], v[138:141], v[186:189], v[28:31]
	v_mfma_f32_16x16x32_bf16 v[20:23], v[146:149], v[186:189], v[20:23]
	v_mfma_f32_16x16x32_bf16 v[12:15], v[138:141], v[212:215], v[12:15]
	v_mfma_f32_16x16x32_bf16 v[0:3], v[146:149], v[212:215], v[0:3]
	s_setprio 0
	s_setprio 1
	v_mfma_f32_16x16x32_bf16 v[58:61], v[150:153], v[166:169], v[58:61]
	v_mfma_f32_16x16x32_bf16 v[50:53], v[158:161], v[166:169], v[50:53]
	v_mfma_f32_16x16x32_bf16 v[40:43], v[150:153], v[174:177], v[40:43]
	v_mfma_f32_16x16x32_bf16 v[32:35], v[158:161], v[174:177], v[32:35]
	v_mfma_f32_16x16x32_bf16 v[24:27], v[150:153], v[182:185], v[24:27]
	v_mfma_f32_16x16x32_bf16 v[16:19], v[158:161], v[182:185], v[16:19]
	v_mfma_f32_16x16x32_bf16 v[8:11], v[150:153], v[208:211], v[8:11]
	v_mfma_f32_16x16x32_bf16 v[4:7], v[158:161], v[208:211], v[4:7]
	v_mfma_f32_16x16x32_bf16 v[58:61], v[154:157], v[170:173], v[58:61]
	v_mfma_f32_16x16x32_bf16 v[50:53], v[162:165], v[170:173], v[50:53]
	v_mfma_f32_16x16x32_bf16 v[40:43], v[154:157], v[178:181], v[40:43]
	v_mfma_f32_16x16x32_bf16 v[32:35], v[162:165], v[178:181], v[32:35]
	v_mfma_f32_16x16x32_bf16 v[24:27], v[154:157], v[186:189], v[24:27]
	v_mfma_f32_16x16x32_bf16 v[16:19], v[162:165], v[186:189], v[16:19]
	v_mfma_f32_16x16x32_bf16 v[8:11], v[154:157], v[212:215], v[8:11]
	v_mfma_f32_16x16x32_bf16 v[4:7], v[162:165], v[212:215], v[4:7]
	s_setprio 0
	s_barrier
	s_add_i32 s45, 0, 0x18000
	s_add_i32 s46, 0, 0x1c000
	v_add_u32_e32 v146, s45, v239
	v_add_u32_e32 v162, s46, v239
	ds_read_b128 v[134:137], v146
	ds_read_b128 v[138:141], v146 offset:1024
	ds_read_b128 v[142:145], v146 offset:2048
	ds_read_b128 v[146:149], v146 offset:3072
	ds_read_b128 v[150:153], v162
	ds_read_b128 v[154:157], v162 offset:1024
	ds_read_b128 v[158:161], v162 offset:2048
	ds_read_b128 v[162:165], v162 offset:3072
	s_add_u32 s26, s26, s50
	s_addc_u32 s27, s27, 0
	s_mov_b32 m0, s34
	v_lshl_add_u64 v[224:225], s[26:27], 0, v[202:203]
	ds_read_b128 v[166:169], v241 offset:32768
	ds_read_b128 v[170:173], v241 offset:33792
	ds_read_b128 v[174:177], v241 offset:34816
	ds_read_b128 v[178:181], v241 offset:35840
	ds_read_b128 v[182:185], v241 offset:36864
	ds_read_b128 v[186:189], v241 offset:37888
	ds_read_b128 v[208:211], v241 offset:38912
	ds_read_b128 v[212:215], v241 offset:39936
	global_load_lds_dwordx4 v[224:225], off
	v_lshl_add_u64 v[224:225], s[26:27], 0, v[200:201]
	s_mov_b32 m0, s35
	s_nop 0
	global_load_lds_dwordx4 v[224:225], off
	s_waitcnt vmcnt(8)
	s_waitcnt lgkmcnt(0)
	s_barrier
	s_setprio 1
	s_waitcnt lgkmcnt(0)
	v_mfma_f32_16x16x32_bf16 v[126:129], v[134:137], v[166:169], v[126:129]
	v_mfma_f32_16x16x32_bf16 v[122:125], v[142:145], v[166:169], v[122:125]
	v_mfma_f32_16x16x32_bf16 v[110:113], v[134:137], v[174:177], v[110:113]
	v_mfma_f32_16x16x32_bf16 v[102:105], v[142:145], v[174:177], v[102:105]
	v_mfma_f32_16x16x32_bf16 v[94:97], v[134:137], v[182:185], v[94:97]
	v_mfma_f32_16x16x32_bf16 v[86:89], v[142:145], v[182:185], v[86:89]
	v_mfma_f32_16x16x32_bf16 v[78:81], v[134:137], v[208:211], v[78:81]
	v_mfma_f32_16x16x32_bf16 v[70:73], v[142:145], v[208:211], v[70:73]
	v_mfma_f32_16x16x32_bf16 v[126:129], v[138:141], v[170:173], v[126:129]
	v_mfma_f32_16x16x32_bf16 v[122:125], v[146:149], v[170:173], v[122:125]
	v_mfma_f32_16x16x32_bf16 v[110:113], v[138:141], v[178:181], v[110:113]
	v_mfma_f32_16x16x32_bf16 v[102:105], v[146:149], v[178:181], v[102:105]
	v_mfma_f32_16x16x32_bf16 v[94:97], v[138:141], v[186:189], v[94:97]
	v_mfma_f32_16x16x32_bf16 v[86:89], v[146:149], v[186:189], v[86:89]
	v_mfma_f32_16x16x32_bf16 v[78:81], v[138:141], v[212:215], v[78:81]
	v_mfma_f32_16x16x32_bf16 v[70:73], v[146:149], v[212:215], v[70:73]
	s_setprio 0
	s_setprio 1
	v_mfma_f32_16x16x32_bf16 v[118:121], v[150:153], v[166:169], v[118:121]
	v_mfma_f32_16x16x32_bf16 v[114:117], v[158:161], v[166:169], v[114:117]
	v_mfma_f32_16x16x32_bf16 v[106:109], v[150:153], v[174:177], v[106:109]
	v_mfma_f32_16x16x32_bf16 v[98:101], v[158:161], v[174:177], v[98:101]
	v_mfma_f32_16x16x32_bf16 v[90:93], v[150:153], v[182:185], v[90:93]
	v_mfma_f32_16x16x32_bf16 v[82:85], v[158:161], v[182:185], v[82:85]
	v_mfma_f32_16x16x32_bf16 v[74:77], v[150:153], v[208:211], v[74:77]
	v_mfma_f32_16x16x32_bf16 v[66:69], v[158:161], v[208:211], v[66:69]
	v_mfma_f32_16x16x32_bf16 v[118:121], v[154:157], v[170:173], v[118:121]
	v_mfma_f32_16x16x32_bf16 v[114:117], v[162:165], v[170:173], v[114:117]
	v_mfma_f32_16x16x32_bf16 v[106:109], v[154:157], v[178:181], v[106:109]
	v_mfma_f32_16x16x32_bf16 v[98:101], v[162:165], v[178:181], v[98:101]
	v_mfma_f32_16x16x32_bf16 v[90:93], v[154:157], v[186:189], v[90:93]
	v_mfma_f32_16x16x32_bf16 v[82:85], v[162:165], v[186:189], v[82:85]
	v_mfma_f32_16x16x32_bf16 v[74:77], v[154:157], v[212:215], v[74:77]
	v_mfma_f32_16x16x32_bf16 v[66:69], v[162:165], v[212:215], v[66:69]
	s_setprio 0
	s_barrier
	s_add_i32 s26, s45, s29
	v_lshl_add_u64 v[216:217], v[216:217], 0, s[70:71]
	s_mov_b32 m0, s26
	ds_read_b128 v[166:169], v241 offset:49152
	ds_read_b128 v[170:173], v241 offset:50176
	ds_read_b128 v[174:177], v241 offset:51200
	ds_read_b128 v[178:181], v241 offset:52224
	ds_read_b128 v[182:185], v241 offset:53248
	ds_read_b128 v[186:189], v241 offset:54272
	ds_read_b128 v[208:211], v241 offset:55296
	ds_read_b128 v[212:215], v241 offset:56320
	global_load_lds_dwordx4 v[216:217], off
	s_add_i32 m0, s26, 0x2000
	s_add_u32 s24, s24, 0xb0080
	v_lshl_add_u64 v[216:217], v[218:219], 0, s[70:71]
	s_addc_u32 s25, s25, 0
	s_add_i32 s26, s46, s29
	global_load_lds_dwordx4 v[216:217], off
	v_lshl_add_u64 v[216:217], s[24:25], 0, v[48:49]
	s_mov_b32 m0, s26
	s_nop 0
	global_load_lds_dwordx4 v[216:217], off
	v_lshl_add_u64 v[216:217], s[24:25], 0, v[198:199]
	s_add_i32 m0, s26, 0x2000
	s_nop 0
	global_load_lds_dwordx4 v[216:217], off
	v_add_co_u32_e32 v216, vcc, 0x8000, v220
	v_addc_co_u32_e32 v217, vcc, 0, v221, vcc
	s_mov_b32 m0, s40
	s_nop 0
	global_load_lds_dwordx4 v[216:217], off
	v_add_co_u32_e32 v216, vcc, 0x8000, v222
	v_addc_co_u32_e32 v217, vcc, 0, v223, vcc
	s_mov_b32 m0, s41
	s_nop 0
	global_load_lds_dwordx4 v[216:217], off
	s_waitcnt vmcnt(8)
	s_waitcnt lgkmcnt(0)
	s_barrier
	s_setprio 1
	s_waitcnt lgkmcnt(0)
	v_mfma_f32_16x16x32_bf16 v[62:65], v[134:137], v[166:169], v[62:65]
	v_mfma_f32_16x16x32_bf16 v[54:57], v[142:145], v[166:169], v[54:57]
	v_mfma_f32_16x16x32_bf16 v[44:47], v[134:137], v[174:177], v[44:47]
	v_mfma_f32_16x16x32_bf16 v[36:39], v[142:145], v[174:177], v[36:39]
	v_mfma_f32_16x16x32_bf16 v[28:31], v[134:137], v[182:185], v[28:31]
	v_mfma_f32_16x16x32_bf16 v[20:23], v[142:145], v[182:185], v[20:23]
	v_mfma_f32_16x16x32_bf16 v[12:15], v[134:137], v[208:211], v[12:15]
	v_mfma_f32_16x16x32_bf16 v[0:3], v[142:145], v[208:211], v[0:3]
	v_mfma_f32_16x16x32_bf16 v[62:65], v[138:141], v[170:173], v[62:65]
	v_mfma_f32_16x16x32_bf16 v[54:57], v[146:149], v[170:173], v[54:57]
	v_mfma_f32_16x16x32_bf16 v[44:47], v[138:141], v[178:181], v[44:47]
	v_mfma_f32_16x16x32_bf16 v[36:39], v[146:149], v[178:181], v[36:39]
	v_mfma_f32_16x16x32_bf16 v[28:31], v[138:141], v[186:189], v[28:31]
	v_mfma_f32_16x16x32_bf16 v[20:23], v[146:149], v[186:189], v[20:23]
	v_mfma_f32_16x16x32_bf16 v[12:15], v[138:141], v[212:215], v[12:15]
	v_mfma_f32_16x16x32_bf16 v[0:3], v[146:149], v[212:215], v[0:3]
	s_setprio 0
	s_setprio 1
	v_mfma_f32_16x16x32_bf16 v[58:61], v[150:153], v[166:169], v[58:61]
	v_mfma_f32_16x16x32_bf16 v[50:53], v[158:161], v[166:169], v[50:53]
	v_mfma_f32_16x16x32_bf16 v[40:43], v[150:153], v[174:177], v[40:43]
	v_mfma_f32_16x16x32_bf16 v[32:35], v[158:161], v[174:177], v[32:35]
	v_mfma_f32_16x16x32_bf16 v[24:27], v[150:153], v[182:185], v[24:27]
	v_mfma_f32_16x16x32_bf16 v[16:19], v[158:161], v[182:185], v[16:19]
	v_mfma_f32_16x16x32_bf16 v[8:11], v[150:153], v[208:211], v[8:11]
	v_mfma_f32_16x16x32_bf16 v[4:7], v[158:161], v[208:211], v[4:7]
	v_mfma_f32_16x16x32_bf16 v[58:61], v[154:157], v[170:173], v[58:61]
	v_mfma_f32_16x16x32_bf16 v[50:53], v[162:165], v[170:173], v[50:53]
	v_mfma_f32_16x16x32_bf16 v[40:43], v[154:157], v[178:181], v[40:43]
	v_mfma_f32_16x16x32_bf16 v[32:35], v[162:165], v[178:181], v[32:35]
	v_mfma_f32_16x16x32_bf16 v[24:27], v[154:157], v[186:189], v[24:27]
	v_mfma_f32_16x16x32_bf16 v[16:19], v[162:165], v[186:189], v[16:19]
	v_mfma_f32_16x16x32_bf16 v[8:11], v[154:157], v[212:215], v[8:11]
	v_mfma_f32_16x16x32_bf16 v[4:7], v[162:165], v[212:215], v[4:7]
	s_setprio 0
	s_barrier
	s_add_i32 s44, s44, 2
	s_add_u32 s22, s22, 0x100
	s_addc_u32 s23, s23, 0
	s_cmp_gt_u32 s44, 41
	s_cbranch_scc0 .LBB0_220
	s_and_b64 vcc, exec, s[14:15]
	s_cbranch_vccz .LBB0_223
	s_barrier
